# E31: E30 + ds_read base addresses via one pre-header VGPR and offset immediates (4 VALU adds per iteration removed in each K-loop)
# baseline (speedup 1.0000x reference)
.LBB0_199:
	s_ashr_i32 s77, s76, 31
	s_lshl_b64 s[6:7], s[76:77], 19
	s_add_u32 s78, s25, s6
	s_addc_u32 s79, s73, s7
	s_and_b64 s[6:7], s[80:81], exec
	s_cselect_b32 s20, s79, s1
	s_cselect_b32 s21, s78, s0
	s_ashr_i32 s75, s74, 31
	s_lshl_b64 s[6:7], s[74:75], 19
	s_add_u32 s82, s18, s6
	s_addc_u32 s83, s19, s7
	s_and_b64 s[6:7], s[80:81], exec
	s_cselect_b32 s22, s83, s5
	s_cselect_b32 s23, s82, s4
	s_add_u32 s0, s0, 0x40080
	s_addc_u32 s1, s1, 0
	s_add_u32 s37, s4, 0x100
	v_mov_b32_e32 v4, 0
	s_addc_u32 s40, s5, 0
	s_mov_b32 s41, -2
	v_mov_b32_e32 v5, v4
	v_mov_b32_e32 v6, v4
	v_mov_b32_e32 v7, v4
	v_mov_b32_e32 v8, v4
	v_mov_b32_e32 v9, v4
	v_mov_b32_e32 v10, v4
	v_mov_b32_e32 v11, v4
	v_mov_b32_e32 v20, v4
	v_mov_b32_e32 v21, v4
	v_mov_b32_e32 v22, v4
	v_mov_b32_e32 v23, v4
	v_mov_b32_e32 v24, v4
	v_mov_b32_e32 v25, v4
	v_mov_b32_e32 v26, v4
	v_mov_b32_e32 v27, v4
	v_mov_b32_e32 v36, v4
	v_mov_b32_e32 v37, v4
	v_mov_b32_e32 v38, v4
	v_mov_b32_e32 v39, v4
	v_mov_b32_e32 v40, v4
	v_mov_b32_e32 v41, v4
	v_mov_b32_e32 v42, v4
	v_mov_b32_e32 v43, v4
	v_mov_b32_e32 v52, v4
	v_mov_b32_e32 v53, v4
	v_mov_b32_e32 v54, v4
	v_mov_b32_e32 v55, v4
	v_mov_b32_e32 v56, v4
	v_mov_b32_e32 v57, v4
	v_mov_b32_e32 v58, v4
	v_mov_b32_e32 v59, v4
	v_mov_b32_e32 v12, v4
	v_mov_b32_e32 v13, v4
	v_mov_b32_e32 v14, v4
	v_mov_b32_e32 v15, v4
	v_mov_b32_e32 v16, v4
	v_mov_b32_e32 v17, v4
	v_mov_b32_e32 v18, v4
	v_mov_b32_e32 v19, v4
	v_mov_b32_e32 v28, v4
	v_mov_b32_e32 v29, v4
	v_mov_b32_e32 v30, v4
	v_mov_b32_e32 v31, v4
	v_mov_b32_e32 v32, v4
	v_mov_b32_e32 v33, v4
	v_mov_b32_e32 v34, v4
	v_mov_b32_e32 v35, v4
	v_mov_b32_e32 v44, v4
	v_mov_b32_e32 v45, v4
	v_mov_b32_e32 v46, v4
	v_mov_b32_e32 v47, v4
	v_mov_b32_e32 v48, v4
	v_mov_b32_e32 v49, v4
	v_mov_b32_e32 v50, v4
	v_mov_b32_e32 v51, v4
	v_mov_b32_e32 v60, v4
	v_mov_b32_e32 v61, v4
	v_mov_b32_e32 v62, v4
	v_mov_b32_e32 v63, v4
	v_mov_b32_e32 v64, v4
	v_mov_b32_e32 v65, v4
	v_mov_b32_e32 v66, v4
	v_mov_b32_e32 v67, v4
	v_mov_b32_e32 v68, v4
	v_mov_b32_e32 v69, v4
	v_mov_b32_e32 v70, v4
	v_mov_b32_e32 v71, v4
	v_mov_b32_e32 v72, v4
	v_mov_b32_e32 v73, v4
	v_mov_b32_e32 v74, v4
	v_mov_b32_e32 v75, v4
	v_mov_b32_e32 v84, v4
	v_mov_b32_e32 v85, v4
	v_mov_b32_e32 v86, v4
	v_mov_b32_e32 v87, v4
	v_mov_b32_e32 v88, v4
	v_mov_b32_e32 v89, v4
	v_mov_b32_e32 v90, v4
	v_mov_b32_e32 v91, v4
	v_mov_b32_e32 v100, v4
	v_mov_b32_e32 v101, v4
	v_mov_b32_e32 v102, v4
	v_mov_b32_e32 v103, v4
	v_mov_b32_e32 v104, v4
	v_mov_b32_e32 v105, v4
	v_mov_b32_e32 v106, v4
	v_mov_b32_e32 v107, v4
	v_mov_b32_e32 v116, v4
	v_mov_b32_e32 v117, v4
	v_mov_b32_e32 v118, v4
	v_mov_b32_e32 v119, v4
	v_mov_b32_e32 v120, v4
	v_mov_b32_e32 v121, v4
	v_mov_b32_e32 v122, v4
	v_mov_b32_e32 v123, v4
	v_mov_b32_e32 v76, v4
	v_mov_b32_e32 v77, v4
	v_mov_b32_e32 v78, v4
	v_mov_b32_e32 v79, v4
	v_mov_b32_e32 v80, v4
	v_mov_b32_e32 v81, v4
	v_mov_b32_e32 v82, v4
	v_mov_b32_e32 v83, v4
	v_mov_b32_e32 v92, v4
	v_mov_b32_e32 v93, v4
	v_mov_b32_e32 v94, v4
	v_mov_b32_e32 v95, v4
	v_mov_b32_e32 v96, v4
	v_mov_b32_e32 v97, v4
	v_mov_b32_e32 v98, v4
	v_mov_b32_e32 v99, v4
	v_mov_b32_e32 v108, v4
	v_mov_b32_e32 v109, v4
	v_mov_b32_e32 v110, v4
	v_mov_b32_e32 v111, v4
	v_mov_b32_e32 v112, v4
	v_mov_b32_e32 v113, v4
	v_mov_b32_e32 v114, v4
	v_mov_b32_e32 v115, v4
	v_mov_b32_e32 v124, v4
	v_mov_b32_e32 v125, v4
	v_mov_b32_e32 v126, v4
	v_mov_b32_e32 v127, v4
	v_mov_b32_e32 v128, v4
	v_mov_b32_e32 v129, v4
	v_mov_b32_e32 v130, v4
	v_mov_b32_e32 v131, v4
	s_mov_b64 s[26:27], 0x80
	v_add_u32_e32 v248, 0x10000, v188
.LBB0_200:
	s_add_u32 s4, s0, 0xfffc0080
	s_addc_u32 s5, s1, -1
	s_add_i32 s12, 0, 0x10000
	s_cmp_eq_u32 s41, 12
	s_cselect_b32 s7, s20, s5
	s_cselect_b32 s6, s21, s4
	s_cselect_b32 s5, s22, s40
	s_cselect_b32 s4, s23, s37
	s_add_i32 s13, 0, 0x14000
	ds_read_b128 v[132:135], v248
	ds_read_b128 v[136:139], v248 offset:1024
	ds_read_b128 v[140:143], v248 offset:2048
	ds_read_b128 v[144:147], v248 offset:3072
	ds_read_b128 v[156:159], v248 offset:16384
	ds_read_b128 v[164:167], v248 offset:17408
	ds_read_b128 v[168:171], v248 offset:18432
	ds_read_b128 v[172:175], v248 offset:19456
	s_add_i32 m0, s85, 0xc000
	ds_read_b128 v[176:179], v189
	ds_read_b128 v[180:183], v189 offset:1024
	ds_read_b128 v[190:193], v189 offset:2048
	ds_read_b128 v[194:197], v189 offset:3072
	ds_read_b128 v[198:201], v189 offset:4096
	ds_read_b128 v[202:205], v189 offset:5120
	ds_read_b128 v[206:209], v189 offset:6144
	ds_read_b128 v[230:233], v189 offset:7168
	global_load_lds_dwordx4 v154, s[0:1]
	s_add_i32 m0, s85, 0xe000
	s_nop 0
	global_load_lds_dwordx4 v162, s[0:1]
	s_waitcnt vmcnt(8)
	s_waitcnt lgkmcnt(0)
	s_barrier
	s_setprio 1
	s_waitcnt lgkmcnt(0)
	v_mfma_f32_16x16x32_bf16 v[128:131], v[132:135], v[176:179], v[128:131]
	v_mfma_f32_16x16x32_bf16 v[124:127], v[140:143], v[176:179], v[124:127]
	v_mfma_f32_16x16x32_bf16 v[112:115], v[132:135], v[190:193], v[112:115]
	v_mfma_f32_16x16x32_bf16 v[108:111], v[140:143], v[190:193], v[108:111]
	v_mfma_f32_16x16x32_bf16 v[96:99], v[132:135], v[198:201], v[96:99]
	v_mfma_f32_16x16x32_bf16 v[92:95], v[140:143], v[198:201], v[92:95]
	v_mfma_f32_16x16x32_bf16 v[80:83], v[132:135], v[206:209], v[80:83]
	v_mfma_f32_16x16x32_bf16 v[76:79], v[140:143], v[206:209], v[76:79]
	v_mfma_f32_16x16x32_bf16 v[128:131], v[136:139], v[180:183], v[128:131]
	v_mfma_f32_16x16x32_bf16 v[124:127], v[144:147], v[180:183], v[124:127]
	v_mfma_f32_16x16x32_bf16 v[112:115], v[136:139], v[194:197], v[112:115]
	v_mfma_f32_16x16x32_bf16 v[108:111], v[144:147], v[194:197], v[108:111]
	v_mfma_f32_16x16x32_bf16 v[96:99], v[136:139], v[202:205], v[96:99]
	v_mfma_f32_16x16x32_bf16 v[92:95], v[144:147], v[202:205], v[92:95]
	v_mfma_f32_16x16x32_bf16 v[80:83], v[136:139], v[230:233], v[80:83]
	v_mfma_f32_16x16x32_bf16 v[76:79], v[144:147], v[230:233], v[76:79]
	s_setprio 0
	s_setprio 1
	v_mfma_f32_16x16x32_bf16 v[120:123], v[156:159], v[176:179], v[120:123]
	v_mfma_f32_16x16x32_bf16 v[116:119], v[168:171], v[176:179], v[116:119]
	v_mfma_f32_16x16x32_bf16 v[104:107], v[156:159], v[190:193], v[104:107]
	v_mfma_f32_16x16x32_bf16 v[100:103], v[168:171], v[190:193], v[100:103]
	v_mfma_f32_16x16x32_bf16 v[88:91], v[156:159], v[198:201], v[88:91]
	v_mfma_f32_16x16x32_bf16 v[84:87], v[168:171], v[198:201], v[84:87]
	v_mfma_f32_16x16x32_bf16 v[72:75], v[156:159], v[206:209], v[72:75]
	v_mfma_f32_16x16x32_bf16 v[68:71], v[168:171], v[206:209], v[68:71]
	v_mfma_f32_16x16x32_bf16 v[120:123], v[164:167], v[180:183], v[120:123]
	v_mfma_f32_16x16x32_bf16 v[116:119], v[172:175], v[180:183], v[116:119]
	v_mfma_f32_16x16x32_bf16 v[104:107], v[164:167], v[194:197], v[104:107]
	v_mfma_f32_16x16x32_bf16 v[100:103], v[172:175], v[194:197], v[100:103]
	v_mfma_f32_16x16x32_bf16 v[88:91], v[164:167], v[202:205], v[88:91]
	v_mfma_f32_16x16x32_bf16 v[84:87], v[172:175], v[202:205], v[84:87]
	v_mfma_f32_16x16x32_bf16 v[72:75], v[164:167], v[230:233], v[72:75]
	v_mfma_f32_16x16x32_bf16 v[68:71], v[172:175], v[230:233], v[68:71]
	s_setprio 0
	s_barrier
	s_add_i32 s12, s12, s24
	v_lshl_add_u64 v[160:161], s[4:5], 0, v[148:149]
	s_mov_b32 m0, s12
	ds_read_b128 v[176:179], v189 offset:16384
	ds_read_b128 v[180:183], v189 offset:17408
	ds_read_b128 v[190:193], v189 offset:18432
	ds_read_b128 v[194:197], v189 offset:19456
	ds_read_b128 v[198:201], v189 offset:20480
	ds_read_b128 v[202:205], v189 offset:21504
	ds_read_b128 v[206:209], v189 offset:22528
	ds_read_b128 v[230:233], v189 offset:23552
	global_load_lds_dwordx4 v[160:161], off
	s_add_i32 m0, s12, 0x2000
	s_add_u32 vcc_lo, s4, 0x10000
	v_lshl_add_u64 v[184:185], s[4:5], 0, v[152:153]
	s_addc_u32 vcc_hi, s5, 0
	s_add_i32 s12, s13, s24
	global_load_lds_dwordx4 v[184:185], off
	s_mov_b32 m0, s12
	v_lshl_add_u64 v[240:241], s[6:7], 0, v[150:151]
	global_load_lds_dwordx4 v148, vcc
	s_add_i32 m0, s12, 0x2000
	s_nop 0
	global_load_lds_dwordx4 v152, vcc
	v_lshl_add_u64 v[234:235], s[6:7], 0, v[0:1]
	s_mov_b32 m0, s85
	s_nop 0
	global_load_lds_dwordx4 v[234:235], off
	s_mov_b32 m0, s87
	s_nop 0
	global_load_lds_dwordx4 v[240:241], off
	s_waitcnt vmcnt(8)
	s_waitcnt lgkmcnt(0)
	s_barrier
	s_setprio 1
	s_waitcnt lgkmcnt(0)
	v_mfma_f32_16x16x32_bf16 v[64:67], v[132:135], v[176:179], v[64:67]
	v_mfma_f32_16x16x32_bf16 v[60:63], v[140:143], v[176:179], v[60:63]
	v_mfma_f32_16x16x32_bf16 v[48:51], v[132:135], v[190:193], v[48:51]
	v_mfma_f32_16x16x32_bf16 v[44:47], v[140:143], v[190:193], v[44:47]
	v_mfma_f32_16x16x32_bf16 v[32:35], v[132:135], v[198:201], v[32:35]
	v_mfma_f32_16x16x32_bf16 v[28:31], v[140:143], v[198:201], v[28:31]
	v_mfma_f32_16x16x32_bf16 v[16:19], v[132:135], v[206:209], v[16:19]
	v_mfma_f32_16x16x32_bf16 v[12:15], v[140:143], v[206:209], v[12:15]
	v_mfma_f32_16x16x32_bf16 v[64:67], v[136:139], v[180:183], v[64:67]
	v_mfma_f32_16x16x32_bf16 v[60:63], v[144:147], v[180:183], v[60:63]
	v_mfma_f32_16x16x32_bf16 v[48:51], v[136:139], v[194:197], v[48:51]
	v_mfma_f32_16x16x32_bf16 v[44:47], v[144:147], v[194:197], v[44:47]
	v_mfma_f32_16x16x32_bf16 v[32:35], v[136:139], v[202:205], v[32:35]
	v_mfma_f32_16x16x32_bf16 v[28:31], v[144:147], v[202:205], v[28:31]
	v_mfma_f32_16x16x32_bf16 v[16:19], v[136:139], v[230:233], v[16:19]
	v_mfma_f32_16x16x32_bf16 v[12:15], v[144:147], v[230:233], v[12:15]
	s_setprio 0
	s_setprio 1
	v_mfma_f32_16x16x32_bf16 v[56:59], v[156:159], v[176:179], v[56:59]
	v_mfma_f32_16x16x32_bf16 v[52:55], v[168:171], v[176:179], v[52:55]
	v_mfma_f32_16x16x32_bf16 v[40:43], v[156:159], v[190:193], v[40:43]
	v_mfma_f32_16x16x32_bf16 v[36:39], v[168:171], v[190:193], v[36:39]
	v_mfma_f32_16x16x32_bf16 v[24:27], v[156:159], v[198:201], v[24:27]
	v_mfma_f32_16x16x32_bf16 v[20:23], v[168:171], v[198:201], v[20:23]
	v_mfma_f32_16x16x32_bf16 v[8:11], v[156:159], v[206:209], v[8:11]
	v_mfma_f32_16x16x32_bf16 v[4:7], v[168:171], v[206:209], v[4:7]
	v_mfma_f32_16x16x32_bf16 v[56:59], v[164:167], v[180:183], v[56:59]
	v_mfma_f32_16x16x32_bf16 v[52:55], v[172:175], v[180:183], v[52:55]
	v_mfma_f32_16x16x32_bf16 v[40:43], v[164:167], v[194:197], v[40:43]
	v_mfma_f32_16x16x32_bf16 v[36:39], v[172:175], v[194:197], v[36:39]
	v_mfma_f32_16x16x32_bf16 v[24:27], v[164:167], v[202:205], v[24:27]
	v_mfma_f32_16x16x32_bf16 v[20:23], v[172:175], v[202:205], v[20:23]
	v_mfma_f32_16x16x32_bf16 v[8:11], v[164:167], v[230:233], v[8:11]
	v_mfma_f32_16x16x32_bf16 v[4:7], v[172:175], v[230:233], v[4:7]
	s_setprio 0
	s_barrier
	s_add_i32 s12, 0, 0x18000
	s_add_i32 s13, 0, 0x1c000
	ds_read_b128 v[132:135], v248 offset:32768
	ds_read_b128 v[136:139], v248 offset:33792
	ds_read_b128 v[140:143], v248 offset:34816
	ds_read_b128 v[144:147], v248 offset:35840
	ds_read_b128 v[156:159], v248 offset:49152
	ds_read_b128 v[164:167], v248 offset:50176
	ds_read_b128 v[168:171], v248 offset:51200
	ds_read_b128 v[172:175], v248 offset:52224
	s_add_u32 s6, s6, 0x40000
	s_addc_u32 s7, s7, 0
	s_mov_b32 m0, s88
	ds_read_b128 v[176:179], v189 offset:32768
	ds_read_b128 v[180:183], v189 offset:33792
	ds_read_b128 v[190:193], v189 offset:34816
	ds_read_b128 v[194:197], v189 offset:35840
	ds_read_b128 v[198:201], v189 offset:36864
	ds_read_b128 v[202:205], v189 offset:37888
	ds_read_b128 v[206:209], v189 offset:38912
	ds_read_b128 v[230:233], v189 offset:39936
	global_load_lds_dwordx4 v0, s[6:7]
	s_mov_b32 m0, s89
	s_nop 0
	global_load_lds_dwordx4 v150, s[6:7]
	s_waitcnt vmcnt(8)
	s_waitcnt lgkmcnt(0)
	s_barrier
	s_setprio 1
	s_waitcnt lgkmcnt(0)
	v_mfma_f32_16x16x32_bf16 v[128:131], v[132:135], v[176:179], v[128:131]
	v_mfma_f32_16x16x32_bf16 v[124:127], v[140:143], v[176:179], v[124:127]
	v_mfma_f32_16x16x32_bf16 v[112:115], v[132:135], v[190:193], v[112:115]
	v_mfma_f32_16x16x32_bf16 v[108:111], v[140:143], v[190:193], v[108:111]
	v_mfma_f32_16x16x32_bf16 v[96:99], v[132:135], v[198:201], v[96:99]
	v_mfma_f32_16x16x32_bf16 v[92:95], v[140:143], v[198:201], v[92:95]
	v_mfma_f32_16x16x32_bf16 v[80:83], v[132:135], v[206:209], v[80:83]
	v_mfma_f32_16x16x32_bf16 v[76:79], v[140:143], v[206:209], v[76:79]
	v_mfma_f32_16x16x32_bf16 v[128:131], v[136:139], v[180:183], v[128:131]
	v_mfma_f32_16x16x32_bf16 v[124:127], v[144:147], v[180:183], v[124:127]
	v_mfma_f32_16x16x32_bf16 v[112:115], v[136:139], v[194:197], v[112:115]
	v_mfma_f32_16x16x32_bf16 v[108:111], v[144:147], v[194:197], v[108:111]
	v_mfma_f32_16x16x32_bf16 v[96:99], v[136:139], v[202:205], v[96:99]
	v_mfma_f32_16x16x32_bf16 v[92:95], v[144:147], v[202:205], v[92:95]
	v_mfma_f32_16x16x32_bf16 v[80:83], v[136:139], v[230:233], v[80:83]
	v_mfma_f32_16x16x32_bf16 v[76:79], v[144:147], v[230:233], v[76:79]
	s_setprio 0
	s_setprio 1
	v_mfma_f32_16x16x32_bf16 v[120:123], v[156:159], v[176:179], v[120:123]
	v_mfma_f32_16x16x32_bf16 v[116:119], v[168:171], v[176:179], v[116:119]
	v_mfma_f32_16x16x32_bf16 v[104:107], v[156:159], v[190:193], v[104:107]
	v_mfma_f32_16x16x32_bf16 v[100:103], v[168:171], v[190:193], v[100:103]
	v_mfma_f32_16x16x32_bf16 v[88:91], v[156:159], v[198:201], v[88:91]
	v_mfma_f32_16x16x32_bf16 v[84:87], v[168:171], v[198:201], v[84:87]
	v_mfma_f32_16x16x32_bf16 v[72:75], v[156:159], v[206:209], v[72:75]
	v_mfma_f32_16x16x32_bf16 v[68:71], v[168:171], v[206:209], v[68:71]
	v_mfma_f32_16x16x32_bf16 v[120:123], v[164:167], v[180:183], v[120:123]
	v_mfma_f32_16x16x32_bf16 v[116:119], v[172:175], v[180:183], v[116:119]
	v_mfma_f32_16x16x32_bf16 v[104:107], v[164:167], v[194:197], v[104:107]
	v_mfma_f32_16x16x32_bf16 v[100:103], v[172:175], v[194:197], v[100:103]
	v_mfma_f32_16x16x32_bf16 v[88:91], v[164:167], v[202:205], v[88:91]
	v_mfma_f32_16x16x32_bf16 v[84:87], v[172:175], v[202:205], v[84:87]
	v_mfma_f32_16x16x32_bf16 v[72:75], v[164:167], v[230:233], v[72:75]
	v_mfma_f32_16x16x32_bf16 v[68:71], v[172:175], v[230:233], v[68:71]
	s_setprio 0
	s_barrier
	s_add_i32 s6, s12, s24
	v_lshl_add_u64 v[160:161], v[160:161], 0, s[26:27]
	s_mov_b32 m0, s6
	ds_read_b128 v[176:179], v189 offset:49152
	ds_read_b128 v[180:183], v189 offset:50176
	ds_read_b128 v[190:193], v189 offset:51200
	ds_read_b128 v[194:197], v189 offset:52224
	ds_read_b128 v[198:201], v189 offset:53248
	ds_read_b128 v[202:205], v189 offset:54272
	ds_read_b128 v[206:209], v189 offset:55296
	ds_read_b128 v[230:233], v189 offset:56320
	global_load_lds_dwordx4 v[160:161], off
	s_add_i32 m0, s6, 0x2000
	s_add_u32 s4, s4, 0x10080
	v_lshl_add_u64 v[160:161], v[184:185], 0, s[26:27]
	s_addc_u32 s5, s5, 0
	s_add_i32 s6, s13, s24
	global_load_lds_dwordx4 v[160:161], off
	s_mov_b32 m0, s6
	s_nop 0
	global_load_lds_dwordx4 v148, s[4:5]
	s_add_i32 m0, s6, 0x2000
	s_nop 0
	global_load_lds_dwordx4 v152, s[4:5]
	v_lshl_add_u64 v[160:161], v[234:235], 0, s[26:27]
	s_mov_b32 m0, s91
	s_nop 0
	global_load_lds_dwordx4 v[160:161], off
	v_lshl_add_u64 v[160:161], v[240:241], 0, s[26:27]
	s_mov_b32 m0, s92
	s_nop 0
	global_load_lds_dwordx4 v[160:161], off
	s_waitcnt vmcnt(8)
	s_waitcnt lgkmcnt(0)
	s_barrier
	s_setprio 1
	s_waitcnt lgkmcnt(0)
	v_mfma_f32_16x16x32_bf16 v[64:67], v[132:135], v[176:179], v[64:67]
	v_mfma_f32_16x16x32_bf16 v[60:63], v[140:143], v[176:179], v[60:63]
	v_mfma_f32_16x16x32_bf16 v[48:51], v[132:135], v[190:193], v[48:51]
	v_mfma_f32_16x16x32_bf16 v[44:47], v[140:143], v[190:193], v[44:47]
	v_mfma_f32_16x16x32_bf16 v[32:35], v[132:135], v[198:201], v[32:35]
	v_mfma_f32_16x16x32_bf16 v[28:31], v[140:143], v[198:201], v[28:31]
	v_mfma_f32_16x16x32_bf16 v[16:19], v[132:135], v[206:209], v[16:19]
	v_mfma_f32_16x16x32_bf16 v[12:15], v[140:143], v[206:209], v[12:15]
	v_mfma_f32_16x16x32_bf16 v[64:67], v[136:139], v[180:183], v[64:67]
	v_mfma_f32_16x16x32_bf16 v[60:63], v[144:147], v[180:183], v[60:63]
	v_mfma_f32_16x16x32_bf16 v[48:51], v[136:139], v[194:197], v[48:51]
	v_mfma_f32_16x16x32_bf16 v[44:47], v[144:147], v[194:197], v[44:47]
	v_mfma_f32_16x16x32_bf16 v[32:35], v[136:139], v[202:205], v[32:35]
	v_mfma_f32_16x16x32_bf16 v[28:31], v[144:147], v[202:205], v[28:31]
	v_mfma_f32_16x16x32_bf16 v[16:19], v[136:139], v[230:233], v[16:19]
	v_mfma_f32_16x16x32_bf16 v[12:15], v[144:147], v[230:233], v[12:15]
	s_setprio 0
	s_setprio 1
	v_mfma_f32_16x16x32_bf16 v[56:59], v[156:159], v[176:179], v[56:59]
	v_mfma_f32_16x16x32_bf16 v[52:55], v[168:171], v[176:179], v[52:55]
	v_mfma_f32_16x16x32_bf16 v[40:43], v[156:159], v[190:193], v[40:43]
	v_mfma_f32_16x16x32_bf16 v[36:39], v[168:171], v[190:193], v[36:39]
	v_mfma_f32_16x16x32_bf16 v[24:27], v[156:159], v[198:201], v[24:27]
	v_mfma_f32_16x16x32_bf16 v[20:23], v[168:171], v[198:201], v[20:23]
	v_mfma_f32_16x16x32_bf16 v[8:11], v[156:159], v[206:209], v[8:11]
	v_mfma_f32_16x16x32_bf16 v[4:7], v[168:171], v[206:209], v[4:7]
	v_mfma_f32_16x16x32_bf16 v[56:59], v[164:167], v[180:183], v[56:59]
	v_mfma_f32_16x16x32_bf16 v[52:55], v[172:175], v[180:183], v[52:55]
	v_mfma_f32_16x16x32_bf16 v[40:43], v[164:167], v[194:197], v[40:43]
	v_mfma_f32_16x16x32_bf16 v[36:39], v[172:175], v[194:197], v[36:39]
	v_mfma_f32_16x16x32_bf16 v[24:27], v[164:167], v[202:205], v[24:27]
	v_mfma_f32_16x16x32_bf16 v[20:23], v[172:175], v[202:205], v[20:23]
	v_mfma_f32_16x16x32_bf16 v[8:11], v[164:167], v[230:233], v[8:11]
	v_mfma_f32_16x16x32_bf16 v[4:7], v[172:175], v[230:233], v[4:7]
	s_setprio 0
	s_barrier
	s_add_i32 s41, s41, 2
	s_add_u32 s0, s0, 0x100
	s_addc_u32 s1, s1, 0
	s_add_u32 s37, s37, 0x100
	s_addc_u32 s40, s40, 0
	s_cmp_gt_u32 s41, 13
	s_cbranch_scc0 .LBB0_200
	s_mov_b64 s[26:27], 0x80
	s_and_b64 vcc, exec, s[66:67]
	s_cbranch_vccz .LBB0_203
	s_barrier

.LBB0_1563:
	s_ashr_i32 s17, s16, 31
	s_lshl_b64 s[18:19], s[16:17], 17
	s_add_u32 s18, s50, s18
	s_addc_u32 s19, s51, s19
	s_and_b64 s[22:23], s[20:21], exec
	s_cselect_b32 s17, s19, s27
	s_cselect_b32 s63, s18, s26
	s_ashr_i32 s15, s14, 31
	s_lshl_b64 s[22:23], s[14:15], 17
	s_add_u32 s22, s46, s22
	s_addc_u32 s23, s47, s23
	s_and_b64 s[28:29], s[20:21], exec
	v_mov_b32_e32 v4, 0
	s_cselect_b32 s15, s23, s25
	s_cselect_b32 s64, s22, s24
	s_mov_b64 s[34:35], 0
	s_mov_b64 s[28:29], -1
	s_mov_b64 s[30:31], 0
	v_mov_b32_e32 v5, v4
	v_mov_b32_e32 v6, v4
	v_mov_b32_e32 v7, v4
	v_mov_b32_e32 v8, v4
	v_mov_b32_e32 v9, v4
	v_mov_b32_e32 v10, v4
	v_mov_b32_e32 v11, v4
	v_mov_b32_e32 v16, v4
	v_mov_b32_e32 v17, v4
	v_mov_b32_e32 v18, v4
	v_mov_b32_e32 v19, v4
	v_mov_b32_e32 v24, v4
	v_mov_b32_e32 v25, v4
	v_mov_b32_e32 v26, v4
	v_mov_b32_e32 v27, v4
	v_mov_b32_e32 v36, v4
	v_mov_b32_e32 v37, v4
	v_mov_b32_e32 v38, v4
	v_mov_b32_e32 v39, v4
	v_mov_b32_e32 v40, v4
	v_mov_b32_e32 v41, v4
	v_mov_b32_e32 v42, v4
	v_mov_b32_e32 v43, v4
	v_mov_b32_e32 v52, v4
	v_mov_b32_e32 v53, v4
	v_mov_b32_e32 v54, v4
	v_mov_b32_e32 v55, v4
	v_mov_b32_e32 v56, v4
	v_mov_b32_e32 v57, v4
	v_mov_b32_e32 v58, v4
	v_mov_b32_e32 v59, v4
	v_mov_b32_e32 v12, v4
	v_mov_b32_e32 v13, v4
	v_mov_b32_e32 v14, v4
	v_mov_b32_e32 v15, v4
	v_mov_b32_e32 v20, v4
	v_mov_b32_e32 v21, v4
	v_mov_b32_e32 v22, v4
	v_mov_b32_e32 v23, v4
	v_mov_b32_e32 v28, v4
	v_mov_b32_e32 v29, v4
	v_mov_b32_e32 v30, v4
	v_mov_b32_e32 v31, v4
	v_mov_b32_e32 v32, v4
	v_mov_b32_e32 v33, v4
	v_mov_b32_e32 v34, v4
	v_mov_b32_e32 v35, v4
	v_mov_b32_e32 v44, v4
	v_mov_b32_e32 v45, v4
	v_mov_b32_e32 v46, v4
	v_mov_b32_e32 v47, v4
	v_mov_b32_e32 v48, v4
	v_mov_b32_e32 v49, v4
	v_mov_b32_e32 v50, v4
	v_mov_b32_e32 v51, v4
	v_mov_b32_e32 v60, v4
	v_mov_b32_e32 v61, v4
	v_mov_b32_e32 v62, v4
	v_mov_b32_e32 v63, v4
	v_mov_b32_e32 v64, v4
	v_mov_b32_e32 v65, v4
	v_mov_b32_e32 v66, v4
	v_mov_b32_e32 v67, v4
	v_mov_b32_e32 v68, v4
	v_mov_b32_e32 v69, v4
	v_mov_b32_e32 v70, v4
	v_mov_b32_e32 v71, v4
	v_mov_b32_e32 v72, v4
	v_mov_b32_e32 v73, v4
	v_mov_b32_e32 v74, v4
	v_mov_b32_e32 v75, v4
	v_mov_b32_e32 v84, v4
	v_mov_b32_e32 v85, v4
	v_mov_b32_e32 v86, v4
	v_mov_b32_e32 v87, v4
	v_mov_b32_e32 v88, v4
	v_mov_b32_e32 v89, v4
	v_mov_b32_e32 v90, v4
	v_mov_b32_e32 v91, v4
	v_mov_b32_e32 v100, v4
	v_mov_b32_e32 v101, v4
	v_mov_b32_e32 v102, v4
	v_mov_b32_e32 v103, v4
	v_mov_b32_e32 v104, v4
	v_mov_b32_e32 v105, v4
	v_mov_b32_e32 v106, v4
	v_mov_b32_e32 v107, v4
	v_mov_b32_e32 v116, v4
	v_mov_b32_e32 v117, v4
	v_mov_b32_e32 v118, v4
	v_mov_b32_e32 v119, v4
	v_mov_b32_e32 v120, v4
	v_mov_b32_e32 v121, v4
	v_mov_b32_e32 v122, v4
	v_mov_b32_e32 v123, v4
	v_mov_b32_e32 v76, v4
	v_mov_b32_e32 v77, v4
	v_mov_b32_e32 v78, v4
	v_mov_b32_e32 v79, v4
	v_mov_b32_e32 v80, v4
	v_mov_b32_e32 v81, v4
	v_mov_b32_e32 v82, v4
	v_mov_b32_e32 v83, v4
	v_mov_b32_e32 v92, v4
	v_mov_b32_e32 v93, v4
	v_mov_b32_e32 v94, v4
	v_mov_b32_e32 v95, v4
	v_mov_b32_e32 v96, v4
	v_mov_b32_e32 v97, v4
	v_mov_b32_e32 v98, v4
	v_mov_b32_e32 v99, v4
	v_mov_b32_e32 v108, v4
	v_mov_b32_e32 v109, v4
	v_mov_b32_e32 v110, v4
	v_mov_b32_e32 v111, v4
	v_mov_b32_e32 v112, v4
	v_mov_b32_e32 v113, v4
	v_mov_b32_e32 v114, v4
	v_mov_b32_e32 v115, v4
	v_mov_b32_e32 v124, v4
	v_mov_b32_e32 v125, v4
	v_mov_b32_e32 v126, v4
	v_mov_b32_e32 v127, v4
	v_mov_b32_e32 v128, v4
	v_mov_b32_e32 v129, v4
	v_mov_b32_e32 v130, v4
	v_mov_b32_e32 v131, v4
	s_mov_b64 s[76:77], 0x80
	v_add_u32_e32 v248, 0x10000, v145
.LBB0_1564:
	s_add_u32 s42, s26, s34
	s_addc_u32 s43, s27, s35
	s_add_u32 s40, s42, 0x100
	s_addc_u32 s41, s43, 0
	s_and_b64 s[38:39], s[30:31], exec
	s_cselect_b32 s39, s17, s41
	s_cselect_b32 s38, s63, s40
	s_add_u32 s34, s24, s34
	s_addc_u32 s35, s25, s35
	s_add_u32 s34, s34, 0x100
	s_addc_u32 s35, s35, 0
	s_add_i32 s73, 0, 0x10000
	s_and_b64 s[30:31], s[30:31], exec
	s_cselect_b32 s41, s15, s35
	s_cselect_b32 s40, s64, s34
	s_add_i32 s31, 0, 0x14000
	s_add_u32 s44, s42, 0x10080
	s_addc_u32 s45, s43, 0
	s_add_i32 s72, s73, s52
	s_add_i32 m0, s53, 0xc000
	s_add_i32 s75, s53, 0xe000
	s_add_i32 s69, s72, 0x2000
	s_add_u32 s42, s40, 0x10000
	ds_read_b128 v[138:141], v248
	ds_read_b128 v[148:151], v248 offset:1024
	ds_read_b128 v[152:155], v248 offset:2048
	ds_read_b128 v[156:159], v248 offset:3072
	s_addc_u32 s43, s41, 0
	s_add_i32 s71, s31, s52
	ds_read_b128 v[160:163], v248 offset:16384
	ds_read_b128 v[164:167], v248 offset:17408
	ds_read_b128 v[168:171], v248 offset:18432
	ds_read_b128 v[172:175], v248 offset:19456
	s_add_i32 s70, s71, 0x2000
	s_add_i32 s68, 0, 0x18000
	s_add_i32 s67, 0, 0x1c000
	s_add_u32 s34, s38, 0x10000
	s_addc_u32 s35, s39, 0
	s_add_i32 s66, s68, s52
	s_add_i32 s65, s66, 0x2000
	s_add_u32 s30, s40, 0x10080
	s_addc_u32 s31, s41, 0
	s_add_i32 s74, s67, s52
	s_add_i32 s73, s74, 0x2000
	ds_read_b128 v[176:179], v146
	ds_read_b128 v[180:183], v146 offset:1024
	ds_read_b128 v[184:187], v146 offset:2048
	ds_read_b128 v[188:191], v146 offset:3072
	ds_read_b128 v[192:195], v146 offset:4096
	ds_read_b128 v[196:199], v146 offset:5120
	ds_read_b128 v[200:203], v146 offset:6144
	ds_read_b128 v[204:207], v146 offset:7168
	global_load_lds_dwordx4 v136, s[44:45]
	s_mov_b32 m0, s75
	s_nop 0
	global_load_lds_dwordx4 v132, s[44:45]
	s_waitcnt vmcnt(8)
	s_waitcnt lgkmcnt(0)
	s_barrier
	s_setprio 1
	s_waitcnt lgkmcnt(0)
	v_mfma_f32_16x16x32_bf16 v[128:131], v[138:141], v[176:179], v[128:131]
	v_mfma_f32_16x16x32_bf16 v[124:127], v[152:155], v[176:179], v[124:127]
	v_mfma_f32_16x16x32_bf16 v[112:115], v[138:141], v[184:187], v[112:115]
	v_mfma_f32_16x16x32_bf16 v[108:111], v[152:155], v[184:187], v[108:111]
	v_mfma_f32_16x16x32_bf16 v[96:99], v[138:141], v[192:195], v[96:99]
	v_mfma_f32_16x16x32_bf16 v[92:95], v[152:155], v[192:195], v[92:95]
	v_mfma_f32_16x16x32_bf16 v[80:83], v[138:141], v[200:203], v[80:83]
	v_mfma_f32_16x16x32_bf16 v[76:79], v[152:155], v[200:203], v[76:79]
	v_mfma_f32_16x16x32_bf16 v[128:131], v[148:151], v[180:183], v[128:131]
	v_mfma_f32_16x16x32_bf16 v[124:127], v[156:159], v[180:183], v[124:127]
	v_mfma_f32_16x16x32_bf16 v[112:115], v[148:151], v[188:191], v[112:115]
	v_mfma_f32_16x16x32_bf16 v[108:111], v[156:159], v[188:191], v[108:111]
	v_mfma_f32_16x16x32_bf16 v[96:99], v[148:151], v[196:199], v[96:99]
	v_mfma_f32_16x16x32_bf16 v[92:95], v[156:159], v[196:199], v[92:95]
	v_mfma_f32_16x16x32_bf16 v[80:83], v[148:151], v[204:207], v[80:83]
	v_mfma_f32_16x16x32_bf16 v[76:79], v[156:159], v[204:207], v[76:79]
	s_setprio 0
	s_setprio 1
	v_mfma_f32_16x16x32_bf16 v[120:123], v[160:163], v[176:179], v[120:123]
	v_mfma_f32_16x16x32_bf16 v[116:119], v[168:171], v[176:179], v[116:119]
	v_mfma_f32_16x16x32_bf16 v[104:107], v[160:163], v[184:187], v[104:107]
	v_mfma_f32_16x16x32_bf16 v[100:103], v[168:171], v[184:187], v[100:103]
	v_mfma_f32_16x16x32_bf16 v[88:91], v[160:163], v[192:195], v[88:91]
	v_mfma_f32_16x16x32_bf16 v[84:87], v[168:171], v[192:195], v[84:87]
	v_mfma_f32_16x16x32_bf16 v[72:75], v[160:163], v[200:203], v[72:75]
	v_mfma_f32_16x16x32_bf16 v[68:71], v[168:171], v[200:203], v[68:71]
	v_mfma_f32_16x16x32_bf16 v[120:123], v[164:167], v[180:183], v[120:123]
	v_mfma_f32_16x16x32_bf16 v[116:119], v[172:175], v[180:183], v[116:119]
	v_mfma_f32_16x16x32_bf16 v[104:107], v[164:167], v[188:191], v[104:107]
	v_mfma_f32_16x16x32_bf16 v[100:103], v[172:175], v[188:191], v[100:103]
	v_mfma_f32_16x16x32_bf16 v[88:91], v[164:167], v[196:199], v[88:91]
	v_mfma_f32_16x16x32_bf16 v[84:87], v[172:175], v[196:199], v[84:87]
	v_mfma_f32_16x16x32_bf16 v[72:75], v[164:167], v[204:207], v[72:75]
	v_mfma_f32_16x16x32_bf16 v[68:71], v[172:175], v[204:207], v[68:71]
	s_setprio 0
	s_barrier
	s_mov_b32 m0, s72
	v_lshl_add_u64 v[142:143], s[40:41], 0, v[134:135]
	ds_read_b128 v[176:179], v146 offset:16384
	ds_read_b128 v[180:183], v146 offset:17408
	ds_read_b128 v[184:187], v146 offset:18432
	ds_read_b128 v[188:191], v146 offset:19456
	ds_read_b128 v[192:195], v146 offset:20480
	ds_read_b128 v[196:199], v146 offset:21504
	ds_read_b128 v[200:203], v146 offset:22528
	ds_read_b128 v[204:207], v146 offset:23552
	global_load_lds_dwordx4 v[142:143], off
	v_lshl_add_u64 v[208:209], s[40:41], 0, v[0:1]
	s_mov_b32 m0, s69
	s_nop 0
	global_load_lds_dwordx4 v[208:209], off
	s_mov_b32 m0, s71
	v_lshl_add_u64 v[232:233], s[38:39], 0, v[132:133]
	global_load_lds_dwordx4 v134, s[42:43]
	s_mov_b32 m0, s70
	s_nop 0
	global_load_lds_dwordx4 v0, s[42:43]
	v_lshl_add_u64 v[230:231], s[38:39], 0, v[136:137]
	s_mov_b32 m0, s53
	s_nop 0
	global_load_lds_dwordx4 v[230:231], off
	s_mov_b32 m0, s54
	s_nop 0
	global_load_lds_dwordx4 v[232:233], off
	s_waitcnt vmcnt(8)
	s_waitcnt lgkmcnt(0)
	s_barrier
	s_setprio 1
	s_waitcnt lgkmcnt(0)
	v_mfma_f32_16x16x32_bf16 v[64:67], v[138:141], v[176:179], v[64:67]
	v_mfma_f32_16x16x32_bf16 v[60:63], v[152:155], v[176:179], v[60:63]
	v_mfma_f32_16x16x32_bf16 v[48:51], v[138:141], v[184:187], v[48:51]
	v_mfma_f32_16x16x32_bf16 v[44:47], v[152:155], v[184:187], v[44:47]
	v_mfma_f32_16x16x32_bf16 v[32:35], v[138:141], v[192:195], v[32:35]
	v_mfma_f32_16x16x32_bf16 v[28:31], v[152:155], v[192:195], v[28:31]
	v_mfma_f32_16x16x32_bf16 v[20:23], v[138:141], v[200:203], v[20:23]
	v_mfma_f32_16x16x32_bf16 v[12:15], v[152:155], v[200:203], v[12:15]
	v_mfma_f32_16x16x32_bf16 v[64:67], v[148:151], v[180:183], v[64:67]
	v_mfma_f32_16x16x32_bf16 v[60:63], v[156:159], v[180:183], v[60:63]
	v_mfma_f32_16x16x32_bf16 v[48:51], v[148:151], v[188:191], v[48:51]
	v_mfma_f32_16x16x32_bf16 v[44:47], v[156:159], v[188:191], v[44:47]
	v_mfma_f32_16x16x32_bf16 v[32:35], v[148:151], v[196:199], v[32:35]
	v_mfma_f32_16x16x32_bf16 v[28:31], v[156:159], v[196:199], v[28:31]
	v_mfma_f32_16x16x32_bf16 v[20:23], v[148:151], v[204:207], v[20:23]
	v_mfma_f32_16x16x32_bf16 v[12:15], v[156:159], v[204:207], v[12:15]
	s_setprio 0
	s_setprio 1
	v_mfma_f32_16x16x32_bf16 v[56:59], v[160:163], v[176:179], v[56:59]
	v_mfma_f32_16x16x32_bf16 v[52:55], v[168:171], v[176:179], v[52:55]
	v_mfma_f32_16x16x32_bf16 v[40:43], v[160:163], v[184:187], v[40:43]
	v_mfma_f32_16x16x32_bf16 v[36:39], v[168:171], v[184:187], v[36:39]
	v_mfma_f32_16x16x32_bf16 v[24:27], v[160:163], v[192:195], v[24:27]
	v_mfma_f32_16x16x32_bf16 v[16:19], v[168:171], v[192:195], v[16:19]
	v_mfma_f32_16x16x32_bf16 v[8:11], v[160:163], v[200:203], v[8:11]
	v_mfma_f32_16x16x32_bf16 v[4:7], v[168:171], v[200:203], v[4:7]
	v_mfma_f32_16x16x32_bf16 v[56:59], v[164:167], v[180:183], v[56:59]
	v_mfma_f32_16x16x32_bf16 v[52:55], v[172:175], v[180:183], v[52:55]
	v_mfma_f32_16x16x32_bf16 v[40:43], v[164:167], v[188:191], v[40:43]
	v_mfma_f32_16x16x32_bf16 v[36:39], v[172:175], v[188:191], v[36:39]
	v_mfma_f32_16x16x32_bf16 v[24:27], v[164:167], v[196:199], v[24:27]
	v_mfma_f32_16x16x32_bf16 v[16:19], v[172:175], v[196:199], v[16:19]
	v_mfma_f32_16x16x32_bf16 v[8:11], v[164:167], v[204:207], v[8:11]
	v_mfma_f32_16x16x32_bf16 v[4:7], v[172:175], v[204:207], v[4:7]
	s_setprio 0
	s_barrier
	ds_read_b128 v[138:141], v248 offset:32768
	ds_read_b128 v[148:151], v248 offset:33792
	ds_read_b128 v[152:155], v248 offset:34816
	ds_read_b128 v[156:159], v248 offset:35840
	ds_read_b128 v[160:163], v248 offset:49152
	ds_read_b128 v[164:167], v248 offset:50176
	ds_read_b128 v[168:171], v248 offset:51200
	ds_read_b128 v[172:175], v248 offset:52224
	s_mov_b32 m0, s55
	ds_read_b128 v[176:179], v146 offset:32768
	ds_read_b128 v[180:183], v146 offset:33792
	ds_read_b128 v[184:187], v146 offset:34816
	ds_read_b128 v[188:191], v146 offset:35840
	ds_read_b128 v[192:195], v146 offset:36864
	ds_read_b128 v[196:199], v146 offset:37888
	ds_read_b128 v[200:203], v146 offset:38912
	ds_read_b128 v[204:207], v146 offset:39936
	global_load_lds_dwordx4 v136, s[34:35]
	s_mov_b32 m0, s56
	s_nop 0
	global_load_lds_dwordx4 v132, s[34:35]
	s_waitcnt vmcnt(8)
	s_waitcnt lgkmcnt(0)
	s_barrier
	s_setprio 1
	s_waitcnt lgkmcnt(0)
	v_mfma_f32_16x16x32_bf16 v[128:131], v[138:141], v[176:179], v[128:131]
	v_mfma_f32_16x16x32_bf16 v[124:127], v[152:155], v[176:179], v[124:127]
	v_mfma_f32_16x16x32_bf16 v[112:115], v[138:141], v[184:187], v[112:115]
	v_mfma_f32_16x16x32_bf16 v[108:111], v[152:155], v[184:187], v[108:111]
	v_mfma_f32_16x16x32_bf16 v[96:99], v[138:141], v[192:195], v[96:99]
	v_mfma_f32_16x16x32_bf16 v[92:95], v[152:155], v[192:195], v[92:95]
	v_mfma_f32_16x16x32_bf16 v[80:83], v[138:141], v[200:203], v[80:83]
	v_mfma_f32_16x16x32_bf16 v[76:79], v[152:155], v[200:203], v[76:79]
	v_mfma_f32_16x16x32_bf16 v[128:131], v[148:151], v[180:183], v[128:131]
	v_mfma_f32_16x16x32_bf16 v[124:127], v[156:159], v[180:183], v[124:127]
	v_mfma_f32_16x16x32_bf16 v[112:115], v[148:151], v[188:191], v[112:115]
	v_mfma_f32_16x16x32_bf16 v[108:111], v[156:159], v[188:191], v[108:111]
	v_mfma_f32_16x16x32_bf16 v[96:99], v[148:151], v[196:199], v[96:99]
	v_mfma_f32_16x16x32_bf16 v[92:95], v[156:159], v[196:199], v[92:95]
	v_mfma_f32_16x16x32_bf16 v[80:83], v[148:151], v[204:207], v[80:83]
	v_mfma_f32_16x16x32_bf16 v[76:79], v[156:159], v[204:207], v[76:79]
	s_setprio 0
	s_setprio 1
	v_mfma_f32_16x16x32_bf16 v[120:123], v[160:163], v[176:179], v[120:123]
	v_mfma_f32_16x16x32_bf16 v[116:119], v[168:171], v[176:179], v[116:119]
	v_mfma_f32_16x16x32_bf16 v[104:107], v[160:163], v[184:187], v[104:107]
	v_mfma_f32_16x16x32_bf16 v[100:103], v[168:171], v[184:187], v[100:103]
	v_mfma_f32_16x16x32_bf16 v[88:91], v[160:163], v[192:195], v[88:91]
	v_mfma_f32_16x16x32_bf16 v[84:87], v[168:171], v[192:195], v[84:87]
	v_mfma_f32_16x16x32_bf16 v[72:75], v[160:163], v[200:203], v[72:75]
	v_mfma_f32_16x16x32_bf16 v[68:71], v[168:171], v[200:203], v[68:71]
	v_mfma_f32_16x16x32_bf16 v[120:123], v[164:167], v[180:183], v[120:123]
	v_mfma_f32_16x16x32_bf16 v[116:119], v[172:175], v[180:183], v[116:119]
	v_mfma_f32_16x16x32_bf16 v[104:107], v[164:167], v[188:191], v[104:107]
	v_mfma_f32_16x16x32_bf16 v[100:103], v[172:175], v[188:191], v[100:103]
	v_mfma_f32_16x16x32_bf16 v[88:91], v[164:167], v[196:199], v[88:91]
	v_mfma_f32_16x16x32_bf16 v[84:87], v[172:175], v[196:199], v[84:87]
	v_mfma_f32_16x16x32_bf16 v[72:75], v[164:167], v[204:207], v[72:75]
	v_mfma_f32_16x16x32_bf16 v[68:71], v[172:175], v[204:207], v[68:71]
	s_setprio 0
	s_barrier
	s_mov_b32 m0, s66
	v_lshl_add_u64 v[142:143], v[142:143], 0, s[76:77]
	ds_read_b128 v[176:179], v146 offset:49152
	ds_read_b128 v[180:183], v146 offset:50176
	ds_read_b128 v[184:187], v146 offset:51200
	ds_read_b128 v[188:191], v146 offset:52224
	ds_read_b128 v[192:195], v146 offset:53248
	ds_read_b128 v[196:199], v146 offset:54272
	ds_read_b128 v[200:203], v146 offset:55296
	ds_read_b128 v[204:207], v146 offset:56320
	global_load_lds_dwordx4 v[142:143], off
	v_lshl_add_u64 v[142:143], v[208:209], 0, s[76:77]
	s_mov_b32 m0, s65
	s_nop 0
	global_load_lds_dwordx4 v[142:143], off
	s_mov_b32 m0, s74
	s_nop 0
	global_load_lds_dwordx4 v134, s[30:31]
	s_mov_b32 m0, s73
	s_nop 0
	global_load_lds_dwordx4 v0, s[30:31]
	v_lshl_add_u64 v[142:143], v[230:231], 0, s[76:77]
	s_mov_b32 m0, s59
	s_nop 0
	global_load_lds_dwordx4 v[142:143], off
	v_lshl_add_u64 v[142:143], v[232:233], 0, s[76:77]
	s_mov_b32 m0, s60
	s_nop 0
	global_load_lds_dwordx4 v[142:143], off
	s_waitcnt vmcnt(8)
	s_waitcnt lgkmcnt(0)
	s_barrier
	s_setprio 1
	s_waitcnt lgkmcnt(0)
	v_mfma_f32_16x16x32_bf16 v[64:67], v[138:141], v[176:179], v[64:67]
	v_mfma_f32_16x16x32_bf16 v[60:63], v[152:155], v[176:179], v[60:63]
	v_mfma_f32_16x16x32_bf16 v[48:51], v[138:141], v[184:187], v[48:51]
	v_mfma_f32_16x16x32_bf16 v[44:47], v[152:155], v[184:187], v[44:47]
	v_mfma_f32_16x16x32_bf16 v[32:35], v[138:141], v[192:195], v[32:35]
	v_mfma_f32_16x16x32_bf16 v[28:31], v[152:155], v[192:195], v[28:31]
	v_mfma_f32_16x16x32_bf16 v[20:23], v[138:141], v[200:203], v[20:23]
	v_mfma_f32_16x16x32_bf16 v[12:15], v[152:155], v[200:203], v[12:15]
	v_mfma_f32_16x16x32_bf16 v[64:67], v[148:151], v[180:183], v[64:67]
	v_mfma_f32_16x16x32_bf16 v[60:63], v[156:159], v[180:183], v[60:63]
	v_mfma_f32_16x16x32_bf16 v[48:51], v[148:151], v[188:191], v[48:51]
	v_mfma_f32_16x16x32_bf16 v[44:47], v[156:159], v[188:191], v[44:47]
	v_mfma_f32_16x16x32_bf16 v[32:35], v[148:151], v[196:199], v[32:35]
	v_mfma_f32_16x16x32_bf16 v[28:31], v[156:159], v[196:199], v[28:31]
	v_mfma_f32_16x16x32_bf16 v[20:23], v[148:151], v[204:207], v[20:23]
	v_mfma_f32_16x16x32_bf16 v[12:15], v[156:159], v[204:207], v[12:15]
	s_setprio 0
	s_setprio 1
	v_mfma_f32_16x16x32_bf16 v[56:59], v[160:163], v[176:179], v[56:59]
	v_mfma_f32_16x16x32_bf16 v[52:55], v[168:171], v[176:179], v[52:55]
	v_mfma_f32_16x16x32_bf16 v[40:43], v[160:163], v[184:187], v[40:43]
	v_mfma_f32_16x16x32_bf16 v[36:39], v[168:171], v[184:187], v[36:39]
	v_mfma_f32_16x16x32_bf16 v[24:27], v[160:163], v[192:195], v[24:27]
	v_mfma_f32_16x16x32_bf16 v[16:19], v[168:171], v[192:195], v[16:19]
	v_mfma_f32_16x16x32_bf16 v[8:11], v[160:163], v[200:203], v[8:11]
	v_mfma_f32_16x16x32_bf16 v[4:7], v[168:171], v[200:203], v[4:7]
	v_mfma_f32_16x16x32_bf16 v[56:59], v[164:167], v[180:183], v[56:59]
	v_mfma_f32_16x16x32_bf16 v[52:55], v[172:175], v[180:183], v[52:55]
	v_mfma_f32_16x16x32_bf16 v[40:43], v[164:167], v[188:191], v[40:43]
	v_mfma_f32_16x16x32_bf16 v[36:39], v[172:175], v[188:191], v[36:39]
	v_mfma_f32_16x16x32_bf16 v[24:27], v[164:167], v[196:199], v[24:27]
	v_mfma_f32_16x16x32_bf16 v[16:19], v[172:175], v[196:199], v[16:19]
	v_mfma_f32_16x16x32_bf16 v[8:11], v[164:167], v[204:207], v[8:11]
	v_mfma_f32_16x16x32_bf16 v[4:7], v[172:175], v[204:207], v[4:7]
	s_setprio 0
	s_barrier
	s_andn2_b64 vcc, exec, s[28:29]
	s_mov_b64 s[30:31], -1
	s_mov_b64 s[28:29], 0
	s_mov_b64 s[34:35], 0x100
	s_cbranch_vccz .LBB0_1564
	s_and_b64 vcc, exec, s[8:9]
	s_cbranch_vccz .LBB0_1567
	s_barrier

.LBB0_1648:
	s_ashr_i32 s19, s18, 31
	s_lshl_b64 s[20:21], s[18:19], 19
	s_add_u32 s20, s40, s20
	s_addc_u32 s21, s41, s21
	s_and_b64 s[24:25], s[22:23], exec
	s_cselect_b32 s19, s21, s27
	s_cselect_b32 s53, s20, s26
	s_ashr_i32 s17, s16, 31
	s_lshl_b64 s[24:25], s[16:17], 19
	s_add_u32 s24, s34, s24
	s_addc_u32 s25, s35, s25
	s_and_b64 s[30:31], s[22:23], exec
	s_cselect_b32 s17, s25, s29
	s_cselect_b32 s54, s24, s28
	s_add_u32 s26, s26, 0x40080
	s_addc_u32 s27, s27, 0
	s_add_u32 s55, s28, 0x100
	v_mov_b32_e32 v4, 0
	s_addc_u32 s56, s29, 0
	s_mov_b32 s57, -2
	v_mov_b32_e32 v5, v4
	v_mov_b32_e32 v6, v4
	v_mov_b32_e32 v7, v4
	v_mov_b32_e32 v8, v4
	v_mov_b32_e32 v9, v4
	v_mov_b32_e32 v10, v4
	v_mov_b32_e32 v11, v4
	v_mov_b32_e32 v20, v4
	v_mov_b32_e32 v21, v4
	v_mov_b32_e32 v22, v4
	v_mov_b32_e32 v23, v4
	v_mov_b32_e32 v24, v4
	v_mov_b32_e32 v25, v4
	v_mov_b32_e32 v26, v4
	v_mov_b32_e32 v27, v4
	v_mov_b32_e32 v36, v4
	v_mov_b32_e32 v37, v4
	v_mov_b32_e32 v38, v4
	v_mov_b32_e32 v39, v4
	v_mov_b32_e32 v40, v4
	v_mov_b32_e32 v41, v4
	v_mov_b32_e32 v42, v4
	v_mov_b32_e32 v43, v4
	v_mov_b32_e32 v52, v4
	v_mov_b32_e32 v53, v4
	v_mov_b32_e32 v54, v4
	v_mov_b32_e32 v55, v4
	v_mov_b32_e32 v56, v4
	v_mov_b32_e32 v57, v4
	v_mov_b32_e32 v58, v4
	v_mov_b32_e32 v59, v4
	v_mov_b32_e32 v12, v4
	v_mov_b32_e32 v13, v4
	v_mov_b32_e32 v14, v4
	v_mov_b32_e32 v15, v4
	v_mov_b32_e32 v16, v4
	v_mov_b32_e32 v17, v4
	v_mov_b32_e32 v18, v4
	v_mov_b32_e32 v19, v4
	v_mov_b32_e32 v28, v4
	v_mov_b32_e32 v29, v4
	v_mov_b32_e32 v30, v4
	v_mov_b32_e32 v31, v4
	v_mov_b32_e32 v32, v4
	v_mov_b32_e32 v33, v4
	v_mov_b32_e32 v34, v4
	v_mov_b32_e32 v35, v4
	v_mov_b32_e32 v44, v4
	v_mov_b32_e32 v45, v4
	v_mov_b32_e32 v46, v4
	v_mov_b32_e32 v47, v4
	v_mov_b32_e32 v48, v4
	v_mov_b32_e32 v49, v4
	v_mov_b32_e32 v50, v4
	v_mov_b32_e32 v51, v4
	v_mov_b32_e32 v60, v4
	v_mov_b32_e32 v61, v4
	v_mov_b32_e32 v62, v4
	v_mov_b32_e32 v63, v4
	v_mov_b32_e32 v64, v4
	v_mov_b32_e32 v65, v4
	v_mov_b32_e32 v66, v4
	v_mov_b32_e32 v67, v4
	v_mov_b32_e32 v68, v4
	v_mov_b32_e32 v69, v4
	v_mov_b32_e32 v70, v4
	v_mov_b32_e32 v71, v4
	v_mov_b32_e32 v72, v4
	v_mov_b32_e32 v73, v4
	v_mov_b32_e32 v74, v4
	v_mov_b32_e32 v75, v4
	v_mov_b32_e32 v84, v4
	v_mov_b32_e32 v85, v4
	v_mov_b32_e32 v86, v4
	v_mov_b32_e32 v87, v4
	v_mov_b32_e32 v88, v4
	v_mov_b32_e32 v89, v4
	v_mov_b32_e32 v90, v4
	v_mov_b32_e32 v91, v4
	v_mov_b32_e32 v100, v4
	v_mov_b32_e32 v101, v4
	v_mov_b32_e32 v102, v4
	v_mov_b32_e32 v103, v4
	v_mov_b32_e32 v104, v4
	v_mov_b32_e32 v105, v4
	v_mov_b32_e32 v106, v4
	v_mov_b32_e32 v107, v4
	v_mov_b32_e32 v116, v4
	v_mov_b32_e32 v117, v4
	v_mov_b32_e32 v118, v4
	v_mov_b32_e32 v119, v4
	v_mov_b32_e32 v120, v4
	v_mov_b32_e32 v121, v4
	v_mov_b32_e32 v122, v4
	v_mov_b32_e32 v123, v4
	v_mov_b32_e32 v76, v4
	v_mov_b32_e32 v77, v4
	v_mov_b32_e32 v78, v4
	v_mov_b32_e32 v79, v4
	v_mov_b32_e32 v80, v4
	v_mov_b32_e32 v81, v4
	v_mov_b32_e32 v82, v4
	v_mov_b32_e32 v83, v4
	v_mov_b32_e32 v92, v4
	v_mov_b32_e32 v93, v4
	v_mov_b32_e32 v94, v4
	v_mov_b32_e32 v95, v4
	v_mov_b32_e32 v96, v4
	v_mov_b32_e32 v97, v4
	v_mov_b32_e32 v98, v4
	v_mov_b32_e32 v99, v4
	v_mov_b32_e32 v108, v4
	v_mov_b32_e32 v109, v4
	v_mov_b32_e32 v110, v4
	v_mov_b32_e32 v111, v4
	v_mov_b32_e32 v112, v4
	v_mov_b32_e32 v113, v4
	v_mov_b32_e32 v114, v4
	v_mov_b32_e32 v115, v4
	v_mov_b32_e32 v124, v4
	v_mov_b32_e32 v125, v4
	v_mov_b32_e32 v126, v4
	v_mov_b32_e32 v127, v4
	v_mov_b32_e32 v128, v4
	v_mov_b32_e32 v129, v4
	v_mov_b32_e32 v130, v4
	v_mov_b32_e32 v131, v4
	s_mov_b64 s[62:63], 0x80
	v_add_u32_e32 v248, 0x10000, v157
.LBB0_1649:
	s_add_u32 s28, s26, 0xfffc0080
	s_addc_u32 s29, s27, -1
	s_add_i32 s58, 0, 0x10000
	s_cmp_eq_u32 s57, 12
	s_cselect_b32 s31, s19, s29
	s_cselect_b32 s30, s53, s28
	s_cselect_b32 s29, s17, s56
	s_cselect_b32 s28, s54, s55
	s_add_i32 s60, 0, 0x14000
	ds_read_b128 v[132:135], v248
	ds_read_b128 v[136:139], v248 offset:1024
	ds_read_b128 v[140:143], v248 offset:2048
	ds_read_b128 v[144:147], v248 offset:3072
	ds_read_b128 v[164:167], v248 offset:16384
	ds_read_b128 v[168:171], v248 offset:17408
	ds_read_b128 v[172:175], v248 offset:18432
	ds_read_b128 v[176:179], v248 offset:19456
	s_add_i32 m0, s43, 0xc000
	ds_read_b128 v[180:183], v158
	ds_read_b128 v[184:187], v158 offset:1024
	ds_read_b128 v[188:191], v158 offset:2048
	ds_read_b128 v[192:195], v158 offset:3072
	ds_read_b128 v[196:199], v158 offset:4096
	ds_read_b128 v[200:203], v158 offset:5120
	ds_read_b128 v[204:207], v158 offset:6144
	ds_read_b128 v[230:233], v158 offset:7168
	global_load_lds_dwordx4 v154, s[26:27]
	s_add_i32 m0, s43, 0xe000
	s_nop 0
	global_load_lds_dwordx4 v162, s[26:27]
	s_waitcnt vmcnt(8)
	s_waitcnt lgkmcnt(0)
	s_barrier
	s_setprio 1
	s_waitcnt lgkmcnt(0)
	v_mfma_f32_16x16x32_bf16 v[128:131], v[132:135], v[180:183], v[128:131]
	v_mfma_f32_16x16x32_bf16 v[124:127], v[140:143], v[180:183], v[124:127]
	v_mfma_f32_16x16x32_bf16 v[112:115], v[132:135], v[188:191], v[112:115]
	v_mfma_f32_16x16x32_bf16 v[108:111], v[140:143], v[188:191], v[108:111]
	v_mfma_f32_16x16x32_bf16 v[96:99], v[132:135], v[196:199], v[96:99]
	v_mfma_f32_16x16x32_bf16 v[92:95], v[140:143], v[196:199], v[92:95]
	v_mfma_f32_16x16x32_bf16 v[80:83], v[132:135], v[204:207], v[80:83]
	v_mfma_f32_16x16x32_bf16 v[76:79], v[140:143], v[204:207], v[76:79]
	v_mfma_f32_16x16x32_bf16 v[128:131], v[136:139], v[184:187], v[128:131]
	v_mfma_f32_16x16x32_bf16 v[124:127], v[144:147], v[184:187], v[124:127]
	v_mfma_f32_16x16x32_bf16 v[112:115], v[136:139], v[192:195], v[112:115]
	v_mfma_f32_16x16x32_bf16 v[108:111], v[144:147], v[192:195], v[108:111]
	v_mfma_f32_16x16x32_bf16 v[96:99], v[136:139], v[200:203], v[96:99]
	v_mfma_f32_16x16x32_bf16 v[92:95], v[144:147], v[200:203], v[92:95]
	v_mfma_f32_16x16x32_bf16 v[80:83], v[136:139], v[230:233], v[80:83]
	v_mfma_f32_16x16x32_bf16 v[76:79], v[144:147], v[230:233], v[76:79]
	s_setprio 0
	s_setprio 1
	v_mfma_f32_16x16x32_bf16 v[120:123], v[164:167], v[180:183], v[120:123]
	v_mfma_f32_16x16x32_bf16 v[116:119], v[172:175], v[180:183], v[116:119]
	v_mfma_f32_16x16x32_bf16 v[104:107], v[164:167], v[188:191], v[104:107]
	v_mfma_f32_16x16x32_bf16 v[100:103], v[172:175], v[188:191], v[100:103]
	v_mfma_f32_16x16x32_bf16 v[88:91], v[164:167], v[196:199], v[88:91]
	v_mfma_f32_16x16x32_bf16 v[84:87], v[172:175], v[196:199], v[84:87]
	v_mfma_f32_16x16x32_bf16 v[72:75], v[164:167], v[204:207], v[72:75]
	v_mfma_f32_16x16x32_bf16 v[68:71], v[172:175], v[204:207], v[68:71]
	v_mfma_f32_16x16x32_bf16 v[120:123], v[168:171], v[184:187], v[120:123]
	v_mfma_f32_16x16x32_bf16 v[116:119], v[176:179], v[184:187], v[116:119]
	v_mfma_f32_16x16x32_bf16 v[104:107], v[168:171], v[192:195], v[104:107]
	v_mfma_f32_16x16x32_bf16 v[100:103], v[176:179], v[192:195], v[100:103]
	v_mfma_f32_16x16x32_bf16 v[88:91], v[168:171], v[200:203], v[88:91]
	v_mfma_f32_16x16x32_bf16 v[84:87], v[176:179], v[200:203], v[84:87]
	v_mfma_f32_16x16x32_bf16 v[72:75], v[168:171], v[230:233], v[72:75]
	v_mfma_f32_16x16x32_bf16 v[68:71], v[176:179], v[230:233], v[68:71]
	s_setprio 0
	s_barrier
	s_add_i32 s58, s58, s42
	v_lshl_add_u64 v[160:161], s[28:29], 0, v[150:151]
	s_mov_b32 m0, s58
	ds_read_b128 v[180:183], v158 offset:16384
	ds_read_b128 v[184:187], v158 offset:17408
	ds_read_b128 v[188:191], v158 offset:18432
	ds_read_b128 v[192:195], v158 offset:19456
	ds_read_b128 v[196:199], v158 offset:20480
	ds_read_b128 v[200:203], v158 offset:21504
	ds_read_b128 v[204:207], v158 offset:22528
	ds_read_b128 v[230:233], v158 offset:23552
	global_load_lds_dwordx4 v[160:161], off
	s_add_i32 m0, s58, 0x2000
	s_add_u32 s58, s28, 0x40000
	v_lshl_add_u64 v[208:209], s[28:29], 0, v[0:1]
	s_addc_u32 s59, s29, 0
	s_add_i32 s60, s60, s42
	global_load_lds_dwordx4 v[208:209], off
	s_mov_b32 m0, s60
	v_lshl_add_u64 v[240:241], s[30:31], 0, v[148:149]
	global_load_lds_dwordx4 v150, s[58:59]
	s_add_i32 m0, s60, 0x2000
	s_nop 0
	global_load_lds_dwordx4 v0, s[58:59]
	v_lshl_add_u64 v[234:235], s[30:31], 0, v[152:153]
	s_mov_b32 m0, s43
	s_nop 0
	global_load_lds_dwordx4 v[234:235], off
	s_mov_b32 m0, s44
	s_nop 0
	global_load_lds_dwordx4 v[240:241], off
	s_waitcnt vmcnt(8)
	s_waitcnt lgkmcnt(0)
	s_barrier
	s_setprio 1
	s_waitcnt lgkmcnt(0)
	v_mfma_f32_16x16x32_bf16 v[64:67], v[132:135], v[180:183], v[64:67]
	v_mfma_f32_16x16x32_bf16 v[60:63], v[140:143], v[180:183], v[60:63]
	v_mfma_f32_16x16x32_bf16 v[48:51], v[132:135], v[188:191], v[48:51]
	v_mfma_f32_16x16x32_bf16 v[44:47], v[140:143], v[188:191], v[44:47]
	v_mfma_f32_16x16x32_bf16 v[32:35], v[132:135], v[196:199], v[32:35]
	v_mfma_f32_16x16x32_bf16 v[28:31], v[140:143], v[196:199], v[28:31]
	v_mfma_f32_16x16x32_bf16 v[16:19], v[132:135], v[204:207], v[16:19]
	v_mfma_f32_16x16x32_bf16 v[12:15], v[140:143], v[204:207], v[12:15]
	v_mfma_f32_16x16x32_bf16 v[64:67], v[136:139], v[184:187], v[64:67]
	v_mfma_f32_16x16x32_bf16 v[60:63], v[144:147], v[184:187], v[60:63]
	v_mfma_f32_16x16x32_bf16 v[48:51], v[136:139], v[192:195], v[48:51]
	v_mfma_f32_16x16x32_bf16 v[44:47], v[144:147], v[192:195], v[44:47]
	v_mfma_f32_16x16x32_bf16 v[32:35], v[136:139], v[200:203], v[32:35]
	v_mfma_f32_16x16x32_bf16 v[28:31], v[144:147], v[200:203], v[28:31]
	v_mfma_f32_16x16x32_bf16 v[16:19], v[136:139], v[230:233], v[16:19]
	v_mfma_f32_16x16x32_bf16 v[12:15], v[144:147], v[230:233], v[12:15]
	s_setprio 0
	s_setprio 1
	v_mfma_f32_16x16x32_bf16 v[56:59], v[164:167], v[180:183], v[56:59]
	v_mfma_f32_16x16x32_bf16 v[52:55], v[172:175], v[180:183], v[52:55]
	v_mfma_f32_16x16x32_bf16 v[40:43], v[164:167], v[188:191], v[40:43]
	v_mfma_f32_16x16x32_bf16 v[36:39], v[172:175], v[188:191], v[36:39]
	v_mfma_f32_16x16x32_bf16 v[24:27], v[164:167], v[196:199], v[24:27]
	v_mfma_f32_16x16x32_bf16 v[20:23], v[172:175], v[196:199], v[20:23]
	v_mfma_f32_16x16x32_bf16 v[8:11], v[164:167], v[204:207], v[8:11]
	v_mfma_f32_16x16x32_bf16 v[4:7], v[172:175], v[204:207], v[4:7]
	v_mfma_f32_16x16x32_bf16 v[56:59], v[168:171], v[184:187], v[56:59]
	v_mfma_f32_16x16x32_bf16 v[52:55], v[176:179], v[184:187], v[52:55]
	v_mfma_f32_16x16x32_bf16 v[40:43], v[168:171], v[192:195], v[40:43]
	v_mfma_f32_16x16x32_bf16 v[36:39], v[176:179], v[192:195], v[36:39]
	v_mfma_f32_16x16x32_bf16 v[24:27], v[168:171], v[200:203], v[24:27]
	v_mfma_f32_16x16x32_bf16 v[20:23], v[176:179], v[200:203], v[20:23]
	v_mfma_f32_16x16x32_bf16 v[8:11], v[168:171], v[230:233], v[8:11]
	v_mfma_f32_16x16x32_bf16 v[4:7], v[176:179], v[230:233], v[4:7]
	s_setprio 0
	s_barrier
	s_add_i32 s58, 0, 0x18000
	s_add_i32 s59, 0, 0x1c000
	ds_read_b128 v[132:135], v248 offset:32768
	ds_read_b128 v[136:139], v248 offset:33792
	ds_read_b128 v[140:143], v248 offset:34816
	ds_read_b128 v[144:147], v248 offset:35840
	ds_read_b128 v[164:167], v248 offset:49152
	ds_read_b128 v[168:171], v248 offset:50176
	ds_read_b128 v[172:175], v248 offset:51200
	ds_read_b128 v[176:179], v248 offset:52224
	s_add_u32 s30, s30, 0x40000
	s_addc_u32 s31, s31, 0
	s_mov_b32 m0, s45
	ds_read_b128 v[180:183], v158 offset:32768
	ds_read_b128 v[184:187], v158 offset:33792
	ds_read_b128 v[188:191], v158 offset:34816
	ds_read_b128 v[192:195], v158 offset:35840
	ds_read_b128 v[196:199], v158 offset:36864
	ds_read_b128 v[200:203], v158 offset:37888
	ds_read_b128 v[204:207], v158 offset:38912
	ds_read_b128 v[230:233], v158 offset:39936
	global_load_lds_dwordx4 v152, s[30:31]
	s_mov_b32 m0, s46
	s_nop 0
	global_load_lds_dwordx4 v148, s[30:31]
	s_waitcnt vmcnt(8)
	s_waitcnt lgkmcnt(0)
	s_barrier
	s_setprio 1
	s_waitcnt lgkmcnt(0)
	v_mfma_f32_16x16x32_bf16 v[128:131], v[132:135], v[180:183], v[128:131]
	v_mfma_f32_16x16x32_bf16 v[124:127], v[140:143], v[180:183], v[124:127]
	v_mfma_f32_16x16x32_bf16 v[112:115], v[132:135], v[188:191], v[112:115]
	v_mfma_f32_16x16x32_bf16 v[108:111], v[140:143], v[188:191], v[108:111]
	v_mfma_f32_16x16x32_bf16 v[96:99], v[132:135], v[196:199], v[96:99]
	v_mfma_f32_16x16x32_bf16 v[92:95], v[140:143], v[196:199], v[92:95]
	v_mfma_f32_16x16x32_bf16 v[80:83], v[132:135], v[204:207], v[80:83]
	v_mfma_f32_16x16x32_bf16 v[76:79], v[140:143], v[204:207], v[76:79]
	v_mfma_f32_16x16x32_bf16 v[128:131], v[136:139], v[184:187], v[128:131]
	v_mfma_f32_16x16x32_bf16 v[124:127], v[144:147], v[184:187], v[124:127]
	v_mfma_f32_16x16x32_bf16 v[112:115], v[136:139], v[192:195], v[112:115]
	v_mfma_f32_16x16x32_bf16 v[108:111], v[144:147], v[192:195], v[108:111]
	v_mfma_f32_16x16x32_bf16 v[96:99], v[136:139], v[200:203], v[96:99]
	v_mfma_f32_16x16x32_bf16 v[92:95], v[144:147], v[200:203], v[92:95]
	v_mfma_f32_16x16x32_bf16 v[80:83], v[136:139], v[230:233], v[80:83]
	v_mfma_f32_16x16x32_bf16 v[76:79], v[144:147], v[230:233], v[76:79]
	s_setprio 0
	s_setprio 1
	v_mfma_f32_16x16x32_bf16 v[120:123], v[164:167], v[180:183], v[120:123]
	v_mfma_f32_16x16x32_bf16 v[116:119], v[172:175], v[180:183], v[116:119]
	v_mfma_f32_16x16x32_bf16 v[104:107], v[164:167], v[188:191], v[104:107]
	v_mfma_f32_16x16x32_bf16 v[100:103], v[172:175], v[188:191], v[100:103]
	v_mfma_f32_16x16x32_bf16 v[88:91], v[164:167], v[196:199], v[88:91]
	v_mfma_f32_16x16x32_bf16 v[84:87], v[172:175], v[196:199], v[84:87]
	v_mfma_f32_16x16x32_bf16 v[72:75], v[164:167], v[204:207], v[72:75]
	v_mfma_f32_16x16x32_bf16 v[68:71], v[172:175], v[204:207], v[68:71]
	v_mfma_f32_16x16x32_bf16 v[120:123], v[168:171], v[184:187], v[120:123]
	v_mfma_f32_16x16x32_bf16 v[116:119], v[176:179], v[184:187], v[116:119]
	v_mfma_f32_16x16x32_bf16 v[104:107], v[168:171], v[192:195], v[104:107]
	v_mfma_f32_16x16x32_bf16 v[100:103], v[176:179], v[192:195], v[100:103]
	v_mfma_f32_16x16x32_bf16 v[88:91], v[168:171], v[200:203], v[88:91]
	v_mfma_f32_16x16x32_bf16 v[84:87], v[176:179], v[200:203], v[84:87]
	v_mfma_f32_16x16x32_bf16 v[72:75], v[168:171], v[230:233], v[72:75]
	v_mfma_f32_16x16x32_bf16 v[68:71], v[176:179], v[230:233], v[68:71]
	s_setprio 0
	s_barrier
	s_add_i32 s30, s58, s42
	v_lshl_add_u64 v[160:161], v[160:161], 0, s[62:63]
	s_mov_b32 m0, s30
	ds_read_b128 v[180:183], v158 offset:49152
	ds_read_b128 v[184:187], v158 offset:50176
	ds_read_b128 v[188:191], v158 offset:51200
	ds_read_b128 v[192:195], v158 offset:52224
	ds_read_b128 v[196:199], v158 offset:53248
	ds_read_b128 v[200:203], v158 offset:54272
	ds_read_b128 v[204:207], v158 offset:55296
	ds_read_b128 v[230:233], v158 offset:56320
	global_load_lds_dwordx4 v[160:161], off
	s_add_i32 m0, s30, 0x2000
	s_add_u32 s28, s28, 0x40080
	v_lshl_add_u64 v[160:161], v[208:209], 0, s[62:63]
	s_addc_u32 s29, s29, 0
	s_add_i32 s30, s59, s42
	global_load_lds_dwordx4 v[160:161], off
	s_mov_b32 m0, s30
	s_nop 0
	global_load_lds_dwordx4 v150, s[28:29]
	s_add_i32 m0, s30, 0x2000
	s_nop 0
	global_load_lds_dwordx4 v0, s[28:29]
	v_lshl_add_u64 v[160:161], v[234:235], 0, s[62:63]
	s_mov_b32 m0, s49
	s_nop 0
	global_load_lds_dwordx4 v[160:161], off
	v_lshl_add_u64 v[160:161], v[240:241], 0, s[62:63]
	s_mov_b32 m0, s50
	s_nop 0
	global_load_lds_dwordx4 v[160:161], off
	s_waitcnt vmcnt(8)
	s_waitcnt lgkmcnt(0)
	s_barrier
	s_setprio 1
	s_waitcnt lgkmcnt(0)
	v_mfma_f32_16x16x32_bf16 v[64:67], v[132:135], v[180:183], v[64:67]
	v_mfma_f32_16x16x32_bf16 v[60:63], v[140:143], v[180:183], v[60:63]
	v_mfma_f32_16x16x32_bf16 v[48:51], v[132:135], v[188:191], v[48:51]
	v_mfma_f32_16x16x32_bf16 v[44:47], v[140:143], v[188:191], v[44:47]
	v_mfma_f32_16x16x32_bf16 v[32:35], v[132:135], v[196:199], v[32:35]
	v_mfma_f32_16x16x32_bf16 v[28:31], v[140:143], v[196:199], v[28:31]
	v_mfma_f32_16x16x32_bf16 v[16:19], v[132:135], v[204:207], v[16:19]
	v_mfma_f32_16x16x32_bf16 v[12:15], v[140:143], v[204:207], v[12:15]
	v_mfma_f32_16x16x32_bf16 v[64:67], v[136:139], v[184:187], v[64:67]
	v_mfma_f32_16x16x32_bf16 v[60:63], v[144:147], v[184:187], v[60:63]
	v_mfma_f32_16x16x32_bf16 v[48:51], v[136:139], v[192:195], v[48:51]
	v_mfma_f32_16x16x32_bf16 v[44:47], v[144:147], v[192:195], v[44:47]
	v_mfma_f32_16x16x32_bf16 v[32:35], v[136:139], v[200:203], v[32:35]
	v_mfma_f32_16x16x32_bf16 v[28:31], v[144:147], v[200:203], v[28:31]
	v_mfma_f32_16x16x32_bf16 v[16:19], v[136:139], v[230:233], v[16:19]
	v_mfma_f32_16x16x32_bf16 v[12:15], v[144:147], v[230:233], v[12:15]
	s_setprio 0
	s_setprio 1
	v_mfma_f32_16x16x32_bf16 v[56:59], v[164:167], v[180:183], v[56:59]
	v_mfma_f32_16x16x32_bf16 v[52:55], v[172:175], v[180:183], v[52:55]
	v_mfma_f32_16x16x32_bf16 v[40:43], v[164:167], v[188:191], v[40:43]
	v_mfma_f32_16x16x32_bf16 v[36:39], v[172:175], v[188:191], v[36:39]
	v_mfma_f32_16x16x32_bf16 v[24:27], v[164:167], v[196:199], v[24:27]
	v_mfma_f32_16x16x32_bf16 v[20:23], v[172:175], v[196:199], v[20:23]
	v_mfma_f32_16x16x32_bf16 v[8:11], v[164:167], v[204:207], v[8:11]
	v_mfma_f32_16x16x32_bf16 v[4:7], v[172:175], v[204:207], v[4:7]
	v_mfma_f32_16x16x32_bf16 v[56:59], v[168:171], v[184:187], v[56:59]
	v_mfma_f32_16x16x32_bf16 v[52:55], v[176:179], v[184:187], v[52:55]
	v_mfma_f32_16x16x32_bf16 v[40:43], v[168:171], v[192:195], v[40:43]
	v_mfma_f32_16x16x32_bf16 v[36:39], v[176:179], v[192:195], v[36:39]
	v_mfma_f32_16x16x32_bf16 v[24:27], v[168:171], v[200:203], v[24:27]
	v_mfma_f32_16x16x32_bf16 v[20:23], v[176:179], v[200:203], v[20:23]
	v_mfma_f32_16x16x32_bf16 v[8:11], v[168:171], v[230:233], v[8:11]
	v_mfma_f32_16x16x32_bf16 v[4:7], v[176:179], v[230:233], v[4:7]
	s_setprio 0
	s_barrier
	s_add_i32 s57, s57, 2
	s_add_u32 s26, s26, 0x100
	s_addc_u32 s27, s27, 0
	s_add_u32 s55, s55, 0x100
	s_addc_u32 s56, s56, 0
	s_cmp_gt_u32 s57, 13
	s_cbranch_scc0 .LBB0_1649
	s_and_b64 vcc, exec, s[8:9]
	s_cbranch_vccz .LBB0_1652
	s_barrier

.LBB0_1737:
	s_ashr_i32 s19, s18, 31
	s_lshl_b64 s[20:21], s[18:19], 19
	s_add_u32 s20, s41, s20
	s_addc_u32 s21, s42, s21
	s_and_b64 s[24:25], s[22:23], exec
	s_cselect_b32 s19, s21, s5
	s_cselect_b32 s27, s20, s4
	s_ashr_i32 s17, s16, 31
	s_lshl_b64 s[24:25], s[16:17], 19
	s_add_u32 s24, s8, s24
	s_addc_u32 s25, s9, s25
	s_and_b64 s[34:35], s[22:23], exec
	s_cselect_b32 s17, s25, s31
	s_cselect_b32 s52, s24, s30
	s_add_u32 s4, s4, 0x40080
	s_addc_u32 s5, s5, 0
	s_add_u32 s53, s30, 0x100
	v_mov_b32_e32 v4, 0
	s_addc_u32 s54, s31, 0
	s_mov_b32 s55, -2
	s_waitcnt lgkmcnt(0)
	v_mov_b32_e32 v5, v4
	v_mov_b32_e32 v6, v4
	v_mov_b32_e32 v7, v4
	v_mov_b32_e32 v8, v4
	v_mov_b32_e32 v9, v4
	v_mov_b32_e32 v10, v4
	v_mov_b32_e32 v11, v4
	v_mov_b32_e32 v20, v4
	v_mov_b32_e32 v21, v4
	v_mov_b32_e32 v22, v4
	v_mov_b32_e32 v23, v4
	v_mov_b32_e32 v24, v4
	v_mov_b32_e32 v25, v4
	v_mov_b32_e32 v26, v4
	v_mov_b32_e32 v27, v4
	v_mov_b32_e32 v36, v4
	v_mov_b32_e32 v37, v4
	v_mov_b32_e32 v38, v4
	v_mov_b32_e32 v39, v4
	v_mov_b32_e32 v40, v4
	v_mov_b32_e32 v41, v4
	v_mov_b32_e32 v42, v4
	v_mov_b32_e32 v43, v4
	v_mov_b32_e32 v52, v4
	v_mov_b32_e32 v53, v4
	v_mov_b32_e32 v54, v4
	v_mov_b32_e32 v55, v4
	v_mov_b32_e32 v56, v4
	v_mov_b32_e32 v57, v4
	v_mov_b32_e32 v58, v4
	v_mov_b32_e32 v59, v4
	v_mov_b32_e32 v12, v4
	v_mov_b32_e32 v13, v4
	v_mov_b32_e32 v14, v4
	v_mov_b32_e32 v15, v4
	v_mov_b32_e32 v16, v4
	v_mov_b32_e32 v17, v4
	v_mov_b32_e32 v18, v4
	v_mov_b32_e32 v19, v4
	v_mov_b32_e32 v28, v4
	v_mov_b32_e32 v29, v4
	v_mov_b32_e32 v30, v4
	v_mov_b32_e32 v31, v4
	v_mov_b32_e32 v32, v4
	v_mov_b32_e32 v33, v4
	v_mov_b32_e32 v34, v4
	v_mov_b32_e32 v35, v4
	v_mov_b32_e32 v44, v4
	v_mov_b32_e32 v45, v4
	v_mov_b32_e32 v46, v4
	v_mov_b32_e32 v47, v4
	v_mov_b32_e32 v48, v4
	v_mov_b32_e32 v49, v4
	v_mov_b32_e32 v50, v4
	v_mov_b32_e32 v51, v4
	v_mov_b32_e32 v60, v4
	v_mov_b32_e32 v61, v4
	v_mov_b32_e32 v62, v4
	v_mov_b32_e32 v63, v4
	v_mov_b32_e32 v64, v4
	v_mov_b32_e32 v65, v4
	v_mov_b32_e32 v66, v4
	v_mov_b32_e32 v67, v4
	v_mov_b32_e32 v68, v4
	v_mov_b32_e32 v69, v4
	v_mov_b32_e32 v70, v4
	v_mov_b32_e32 v71, v4
	v_mov_b32_e32 v72, v4
	v_mov_b32_e32 v73, v4
	v_mov_b32_e32 v74, v4
	v_mov_b32_e32 v75, v4
	v_mov_b32_e32 v84, v4
	v_mov_b32_e32 v85, v4
	v_mov_b32_e32 v86, v4
	v_mov_b32_e32 v87, v4
	v_mov_b32_e32 v88, v4
	v_mov_b32_e32 v89, v4
	v_mov_b32_e32 v90, v4
	v_mov_b32_e32 v91, v4
	v_mov_b32_e32 v100, v4
	v_mov_b32_e32 v101, v4
	v_mov_b32_e32 v102, v4
	v_mov_b32_e32 v103, v4
	v_mov_b32_e32 v104, v4
	v_mov_b32_e32 v105, v4
	v_mov_b32_e32 v106, v4
	v_mov_b32_e32 v107, v4
	v_mov_b32_e32 v116, v4
	v_mov_b32_e32 v117, v4
	v_mov_b32_e32 v118, v4
	v_mov_b32_e32 v119, v4
	v_mov_b32_e32 v120, v4
	v_mov_b32_e32 v121, v4
	v_mov_b32_e32 v122, v4
	v_mov_b32_e32 v123, v4
	v_mov_b32_e32 v76, v4
	v_mov_b32_e32 v77, v4
	v_mov_b32_e32 v78, v4
	v_mov_b32_e32 v79, v4
	v_mov_b32_e32 v80, v4
	v_mov_b32_e32 v81, v4
	v_mov_b32_e32 v82, v4
	v_mov_b32_e32 v83, v4
	v_mov_b32_e32 v92, v4
	v_mov_b32_e32 v93, v4
	v_mov_b32_e32 v94, v4
	v_mov_b32_e32 v95, v4
	v_mov_b32_e32 v96, v4
	v_mov_b32_e32 v97, v4
	v_mov_b32_e32 v98, v4
	v_mov_b32_e32 v99, v4
	v_mov_b32_e32 v108, v4
	v_mov_b32_e32 v109, v4
	v_mov_b32_e32 v110, v4
	v_mov_b32_e32 v111, v4
	v_mov_b32_e32 v112, v4
	v_mov_b32_e32 v113, v4
	v_mov_b32_e32 v114, v4
	v_mov_b32_e32 v115, v4
	v_mov_b32_e32 v124, v4
	v_mov_b32_e32 v125, v4
	v_mov_b32_e32 v126, v4
	v_mov_b32_e32 v127, v4
	v_mov_b32_e32 v128, v4
	v_mov_b32_e32 v129, v4
	v_mov_b32_e32 v130, v4
	v_mov_b32_e32 v131, v4
	s_mov_b64 s[60:61], 0x80
	v_add_u32_e32 v248, 0x10000, v155
.LBB0_1738:
	s_add_u32 s30, s4, 0xfffc0080
	s_addc_u32 s31, s5, -1
	s_add_i32 s56, 0, 0x10000
	s_cmp_eq_u32 s55, 12
	s_cselect_b32 s35, s19, s31
	s_cselect_b32 s34, s27, s30
	s_cselect_b32 s31, s17, s54
	s_cselect_b32 s30, s52, s53
	s_add_i32 s58, 0, 0x14000
	ds_read_b128 v[132:135], v248
	ds_read_b128 v[136:139], v248 offset:1024
	ds_read_b128 v[150:153], v248 offset:2048
	ds_read_b128 v[158:161], v248 offset:3072
	ds_read_b128 v[162:165], v248 offset:16384
	ds_read_b128 v[166:169], v248 offset:17408
	ds_read_b128 v[170:173], v248 offset:18432
	ds_read_b128 v[174:177], v248 offset:19456
	s_add_i32 m0, s29, 0xc000
	ds_read_b128 v[178:181], v156
	ds_read_b128 v[182:185], v156 offset:1024
	ds_read_b128 v[186:189], v156 offset:2048
	ds_read_b128 v[190:193], v156 offset:3072
	ds_read_b128 v[194:197], v156 offset:4096
	ds_read_b128 v[198:201], v156 offset:5120
	ds_read_b128 v[202:205], v156 offset:6144
	ds_read_b128 v[206:209], v156 offset:7168
	global_load_lds_dwordx4 v146, s[4:5]
	s_add_i32 m0, s29, 0xe000
	s_nop 0
	global_load_lds_dwordx4 v148, s[4:5]
	s_waitcnt vmcnt(8)
	s_waitcnt lgkmcnt(0)
	s_barrier
	s_setprio 1
	s_waitcnt lgkmcnt(0)
	v_mfma_f32_16x16x32_bf16 v[128:131], v[132:135], v[178:181], v[128:131]
	v_mfma_f32_16x16x32_bf16 v[124:127], v[150:153], v[178:181], v[124:127]
	v_mfma_f32_16x16x32_bf16 v[112:115], v[132:135], v[186:189], v[112:115]
	v_mfma_f32_16x16x32_bf16 v[108:111], v[150:153], v[186:189], v[108:111]
	v_mfma_f32_16x16x32_bf16 v[96:99], v[132:135], v[194:197], v[96:99]
	v_mfma_f32_16x16x32_bf16 v[92:95], v[150:153], v[194:197], v[92:95]
	v_mfma_f32_16x16x32_bf16 v[80:83], v[132:135], v[202:205], v[80:83]
	v_mfma_f32_16x16x32_bf16 v[76:79], v[150:153], v[202:205], v[76:79]
	v_mfma_f32_16x16x32_bf16 v[128:131], v[136:139], v[182:185], v[128:131]
	v_mfma_f32_16x16x32_bf16 v[124:127], v[158:161], v[182:185], v[124:127]
	v_mfma_f32_16x16x32_bf16 v[112:115], v[136:139], v[190:193], v[112:115]
	v_mfma_f32_16x16x32_bf16 v[108:111], v[158:161], v[190:193], v[108:111]
	v_mfma_f32_16x16x32_bf16 v[96:99], v[136:139], v[198:201], v[96:99]
	v_mfma_f32_16x16x32_bf16 v[92:95], v[158:161], v[198:201], v[92:95]
	v_mfma_f32_16x16x32_bf16 v[80:83], v[136:139], v[206:209], v[80:83]
	v_mfma_f32_16x16x32_bf16 v[76:79], v[158:161], v[206:209], v[76:79]
	s_setprio 0
	s_setprio 1
	v_mfma_f32_16x16x32_bf16 v[120:123], v[162:165], v[178:181], v[120:123]
	v_mfma_f32_16x16x32_bf16 v[116:119], v[170:173], v[178:181], v[116:119]
	v_mfma_f32_16x16x32_bf16 v[104:107], v[162:165], v[186:189], v[104:107]
	v_mfma_f32_16x16x32_bf16 v[100:103], v[170:173], v[186:189], v[100:103]
	v_mfma_f32_16x16x32_bf16 v[88:91], v[162:165], v[194:197], v[88:91]
	v_mfma_f32_16x16x32_bf16 v[84:87], v[170:173], v[194:197], v[84:87]
	v_mfma_f32_16x16x32_bf16 v[72:75], v[162:165], v[202:205], v[72:75]
	v_mfma_f32_16x16x32_bf16 v[68:71], v[170:173], v[202:205], v[68:71]
	v_mfma_f32_16x16x32_bf16 v[120:123], v[166:169], v[182:185], v[120:123]
	v_mfma_f32_16x16x32_bf16 v[116:119], v[174:177], v[182:185], v[116:119]
	v_mfma_f32_16x16x32_bf16 v[104:107], v[166:169], v[190:193], v[104:107]
	v_mfma_f32_16x16x32_bf16 v[100:103], v[174:177], v[190:193], v[100:103]
	v_mfma_f32_16x16x32_bf16 v[88:91], v[166:169], v[198:201], v[88:91]
	v_mfma_f32_16x16x32_bf16 v[84:87], v[174:177], v[198:201], v[84:87]
	v_mfma_f32_16x16x32_bf16 v[72:75], v[166:169], v[206:209], v[72:75]
	v_mfma_f32_16x16x32_bf16 v[68:71], v[174:177], v[206:209], v[68:71]
	s_setprio 0
	s_barrier
	s_add_i32 s56, s56, s43
	v_lshl_add_u64 v[230:231], s[30:31], 0, v[140:141]
	s_mov_b32 m0, s56
	ds_read_b128 v[178:181], v156 offset:16384
	ds_read_b128 v[182:185], v156 offset:17408
	ds_read_b128 v[186:189], v156 offset:18432
	ds_read_b128 v[190:193], v156 offset:19456
	ds_read_b128 v[194:197], v156 offset:20480
	ds_read_b128 v[198:201], v156 offset:21504
	ds_read_b128 v[202:205], v156 offset:22528
	ds_read_b128 v[206:209], v156 offset:23552
	global_load_lds_dwordx4 v[230:231], off
	s_add_i32 m0, s56, 0x2000
	s_add_u32 s56, s30, 0x40000
	v_lshl_add_u64 v[232:233], s[30:31], 0, v[144:145]
	s_addc_u32 s57, s31, 0
	s_add_i32 s58, s58, s43
	global_load_lds_dwordx4 v[232:233], off
	s_mov_b32 m0, s58
	v_lshl_add_u64 v[240:241], s[34:35], 0, v[142:143]
	global_load_lds_dwordx4 v140, s[56:57]
	s_add_i32 m0, s58, 0x2000
	s_nop 0
	global_load_lds_dwordx4 v144, s[56:57]
	v_lshl_add_u64 v[234:235], s[34:35], 0, v[0:1]
	s_mov_b32 m0, s29
	s_nop 0
	global_load_lds_dwordx4 v[234:235], off
	s_mov_b32 m0, s44
	s_nop 0
	global_load_lds_dwordx4 v[240:241], off
	s_waitcnt vmcnt(8)
	s_waitcnt lgkmcnt(0)
	s_barrier
	s_setprio 1
	s_waitcnt lgkmcnt(0)
	v_mfma_f32_16x16x32_bf16 v[64:67], v[132:135], v[178:181], v[64:67]
	v_mfma_f32_16x16x32_bf16 v[60:63], v[150:153], v[178:181], v[60:63]
	v_mfma_f32_16x16x32_bf16 v[48:51], v[132:135], v[186:189], v[48:51]
	v_mfma_f32_16x16x32_bf16 v[44:47], v[150:153], v[186:189], v[44:47]
	v_mfma_f32_16x16x32_bf16 v[32:35], v[132:135], v[194:197], v[32:35]
	v_mfma_f32_16x16x32_bf16 v[28:31], v[150:153], v[194:197], v[28:31]
	v_mfma_f32_16x16x32_bf16 v[16:19], v[132:135], v[202:205], v[16:19]
	v_mfma_f32_16x16x32_bf16 v[12:15], v[150:153], v[202:205], v[12:15]
	v_mfma_f32_16x16x32_bf16 v[64:67], v[136:139], v[182:185], v[64:67]
	v_mfma_f32_16x16x32_bf16 v[60:63], v[158:161], v[182:185], v[60:63]
	v_mfma_f32_16x16x32_bf16 v[48:51], v[136:139], v[190:193], v[48:51]
	v_mfma_f32_16x16x32_bf16 v[44:47], v[158:161], v[190:193], v[44:47]
	v_mfma_f32_16x16x32_bf16 v[32:35], v[136:139], v[198:201], v[32:35]
	v_mfma_f32_16x16x32_bf16 v[28:31], v[158:161], v[198:201], v[28:31]
	v_mfma_f32_16x16x32_bf16 v[16:19], v[136:139], v[206:209], v[16:19]
	v_mfma_f32_16x16x32_bf16 v[12:15], v[158:161], v[206:209], v[12:15]
	s_setprio 0
	s_setprio 1
	v_mfma_f32_16x16x32_bf16 v[56:59], v[162:165], v[178:181], v[56:59]
	v_mfma_f32_16x16x32_bf16 v[52:55], v[170:173], v[178:181], v[52:55]
	v_mfma_f32_16x16x32_bf16 v[40:43], v[162:165], v[186:189], v[40:43]
	v_mfma_f32_16x16x32_bf16 v[36:39], v[170:173], v[186:189], v[36:39]
	v_mfma_f32_16x16x32_bf16 v[24:27], v[162:165], v[194:197], v[24:27]
	v_mfma_f32_16x16x32_bf16 v[20:23], v[170:173], v[194:197], v[20:23]
	v_mfma_f32_16x16x32_bf16 v[8:11], v[162:165], v[202:205], v[8:11]
	v_mfma_f32_16x16x32_bf16 v[4:7], v[170:173], v[202:205], v[4:7]
	v_mfma_f32_16x16x32_bf16 v[56:59], v[166:169], v[182:185], v[56:59]
	v_mfma_f32_16x16x32_bf16 v[52:55], v[174:177], v[182:185], v[52:55]
	v_mfma_f32_16x16x32_bf16 v[40:43], v[166:169], v[190:193], v[40:43]
	v_mfma_f32_16x16x32_bf16 v[36:39], v[174:177], v[190:193], v[36:39]
	v_mfma_f32_16x16x32_bf16 v[24:27], v[166:169], v[198:201], v[24:27]
	v_mfma_f32_16x16x32_bf16 v[20:23], v[174:177], v[198:201], v[20:23]
	v_mfma_f32_16x16x32_bf16 v[8:11], v[166:169], v[206:209], v[8:11]
	v_mfma_f32_16x16x32_bf16 v[4:7], v[174:177], v[206:209], v[4:7]
	s_setprio 0
	s_barrier
	s_add_i32 s56, 0, 0x18000
	s_add_i32 s57, 0, 0x1c000
	ds_read_b128 v[132:135], v248 offset:32768
	ds_read_b128 v[136:139], v248 offset:33792
	ds_read_b128 v[150:153], v248 offset:34816
	ds_read_b128 v[158:161], v248 offset:35840
	ds_read_b128 v[162:165], v248 offset:49152
	ds_read_b128 v[166:169], v248 offset:50176
	ds_read_b128 v[170:173], v248 offset:51200
	ds_read_b128 v[174:177], v248 offset:52224
	s_add_u32 s34, s34, 0x40000
	s_addc_u32 s35, s35, 0
	s_mov_b32 m0, s45
	ds_read_b128 v[178:181], v156 offset:32768
	ds_read_b128 v[182:185], v156 offset:33792
	ds_read_b128 v[186:189], v156 offset:34816
	ds_read_b128 v[190:193], v156 offset:35840
	ds_read_b128 v[194:197], v156 offset:36864
	ds_read_b128 v[198:201], v156 offset:37888
	ds_read_b128 v[202:205], v156 offset:38912
	ds_read_b128 v[206:209], v156 offset:39936
	global_load_lds_dwordx4 v0, s[34:35]
	s_mov_b32 m0, s46
	s_nop 0
	global_load_lds_dwordx4 v142, s[34:35]
	s_waitcnt vmcnt(8)
	s_waitcnt lgkmcnt(0)
	s_barrier
	s_setprio 1
	s_waitcnt lgkmcnt(0)
	v_mfma_f32_16x16x32_bf16 v[128:131], v[132:135], v[178:181], v[128:131]
	v_mfma_f32_16x16x32_bf16 v[124:127], v[150:153], v[178:181], v[124:127]
	v_mfma_f32_16x16x32_bf16 v[112:115], v[132:135], v[186:189], v[112:115]
	v_mfma_f32_16x16x32_bf16 v[108:111], v[150:153], v[186:189], v[108:111]
	v_mfma_f32_16x16x32_bf16 v[96:99], v[132:135], v[194:197], v[96:99]
	v_mfma_f32_16x16x32_bf16 v[92:95], v[150:153], v[194:197], v[92:95]
	v_mfma_f32_16x16x32_bf16 v[80:83], v[132:135], v[202:205], v[80:83]
	v_mfma_f32_16x16x32_bf16 v[76:79], v[150:153], v[202:205], v[76:79]
	v_mfma_f32_16x16x32_bf16 v[128:131], v[136:139], v[182:185], v[128:131]
	v_mfma_f32_16x16x32_bf16 v[124:127], v[158:161], v[182:185], v[124:127]
	v_mfma_f32_16x16x32_bf16 v[112:115], v[136:139], v[190:193], v[112:115]
	v_mfma_f32_16x16x32_bf16 v[108:111], v[158:161], v[190:193], v[108:111]
	v_mfma_f32_16x16x32_bf16 v[96:99], v[136:139], v[198:201], v[96:99]
	v_mfma_f32_16x16x32_bf16 v[92:95], v[158:161], v[198:201], v[92:95]
	v_mfma_f32_16x16x32_bf16 v[80:83], v[136:139], v[206:209], v[80:83]
	v_mfma_f32_16x16x32_bf16 v[76:79], v[158:161], v[206:209], v[76:79]
	s_setprio 0
	s_setprio 1
	v_mfma_f32_16x16x32_bf16 v[120:123], v[162:165], v[178:181], v[120:123]
	v_mfma_f32_16x16x32_bf16 v[116:119], v[170:173], v[178:181], v[116:119]
	v_mfma_f32_16x16x32_bf16 v[104:107], v[162:165], v[186:189], v[104:107]
	v_mfma_f32_16x16x32_bf16 v[100:103], v[170:173], v[186:189], v[100:103]
	v_mfma_f32_16x16x32_bf16 v[88:91], v[162:165], v[194:197], v[88:91]
	v_mfma_f32_16x16x32_bf16 v[84:87], v[170:173], v[194:197], v[84:87]
	v_mfma_f32_16x16x32_bf16 v[72:75], v[162:165], v[202:205], v[72:75]
	v_mfma_f32_16x16x32_bf16 v[68:71], v[170:173], v[202:205], v[68:71]
	v_mfma_f32_16x16x32_bf16 v[120:123], v[166:169], v[182:185], v[120:123]
	v_mfma_f32_16x16x32_bf16 v[116:119], v[174:177], v[182:185], v[116:119]
	v_mfma_f32_16x16x32_bf16 v[104:107], v[166:169], v[190:193], v[104:107]
	v_mfma_f32_16x16x32_bf16 v[100:103], v[174:177], v[190:193], v[100:103]
	v_mfma_f32_16x16x32_bf16 v[88:91], v[166:169], v[198:201], v[88:91]
	v_mfma_f32_16x16x32_bf16 v[84:87], v[174:177], v[198:201], v[84:87]
	v_mfma_f32_16x16x32_bf16 v[72:75], v[166:169], v[206:209], v[72:75]
	v_mfma_f32_16x16x32_bf16 v[68:71], v[174:177], v[206:209], v[68:71]
	s_setprio 0
	s_barrier
	s_add_i32 s34, s56, s43
	v_lshl_add_u64 v[230:231], v[230:231], 0, s[60:61]
	s_mov_b32 m0, s34
	ds_read_b128 v[178:181], v156 offset:49152
	ds_read_b128 v[182:185], v156 offset:50176
	ds_read_b128 v[186:189], v156 offset:51200
	ds_read_b128 v[190:193], v156 offset:52224
	ds_read_b128 v[194:197], v156 offset:53248
	ds_read_b128 v[198:201], v156 offset:54272
	ds_read_b128 v[202:205], v156 offset:55296
	ds_read_b128 v[206:209], v156 offset:56320
	global_load_lds_dwordx4 v[230:231], off
	s_add_i32 m0, s34, 0x2000
	s_add_u32 s30, s30, 0x40080
	v_lshl_add_u64 v[230:231], v[232:233], 0, s[60:61]
	s_addc_u32 s31, s31, 0
	s_add_i32 s34, s57, s43
	global_load_lds_dwordx4 v[230:231], off
	s_mov_b32 m0, s34
	s_nop 0
	global_load_lds_dwordx4 v140, s[30:31]
	s_add_i32 m0, s34, 0x2000
	s_nop 0
	global_load_lds_dwordx4 v144, s[30:31]
	v_lshl_add_u64 v[230:231], v[234:235], 0, s[60:61]
	s_mov_b32 m0, s49
	s_nop 0
	global_load_lds_dwordx4 v[230:231], off
	v_lshl_add_u64 v[230:231], v[240:241], 0, s[60:61]
	s_mov_b32 m0, s50
	s_nop 0
	global_load_lds_dwordx4 v[230:231], off
	s_waitcnt vmcnt(8)
	s_waitcnt lgkmcnt(0)
	s_barrier
	s_setprio 1
	s_waitcnt lgkmcnt(0)
	v_mfma_f32_16x16x32_bf16 v[64:67], v[132:135], v[178:181], v[64:67]
	v_mfma_f32_16x16x32_bf16 v[60:63], v[150:153], v[178:181], v[60:63]
	v_mfma_f32_16x16x32_bf16 v[48:51], v[132:135], v[186:189], v[48:51]
	v_mfma_f32_16x16x32_bf16 v[44:47], v[150:153], v[186:189], v[44:47]
	v_mfma_f32_16x16x32_bf16 v[32:35], v[132:135], v[194:197], v[32:35]
	v_mfma_f32_16x16x32_bf16 v[28:31], v[150:153], v[194:197], v[28:31]
	v_mfma_f32_16x16x32_bf16 v[16:19], v[132:135], v[202:205], v[16:19]
	v_mfma_f32_16x16x32_bf16 v[12:15], v[150:153], v[202:205], v[12:15]
	v_mfma_f32_16x16x32_bf16 v[64:67], v[136:139], v[182:185], v[64:67]
	v_mfma_f32_16x16x32_bf16 v[60:63], v[158:161], v[182:185], v[60:63]
	v_mfma_f32_16x16x32_bf16 v[48:51], v[136:139], v[190:193], v[48:51]
	v_mfma_f32_16x16x32_bf16 v[44:47], v[158:161], v[190:193], v[44:47]
	v_mfma_f32_16x16x32_bf16 v[32:35], v[136:139], v[198:201], v[32:35]
	v_mfma_f32_16x16x32_bf16 v[28:31], v[158:161], v[198:201], v[28:31]
	v_mfma_f32_16x16x32_bf16 v[16:19], v[136:139], v[206:209], v[16:19]
	v_mfma_f32_16x16x32_bf16 v[12:15], v[158:161], v[206:209], v[12:15]
	s_setprio 0
	s_setprio 1
	v_mfma_f32_16x16x32_bf16 v[56:59], v[162:165], v[178:181], v[56:59]
	v_mfma_f32_16x16x32_bf16 v[52:55], v[170:173], v[178:181], v[52:55]
	v_mfma_f32_16x16x32_bf16 v[40:43], v[162:165], v[186:189], v[40:43]
	v_mfma_f32_16x16x32_bf16 v[36:39], v[170:173], v[186:189], v[36:39]
	v_mfma_f32_16x16x32_bf16 v[24:27], v[162:165], v[194:197], v[24:27]
	v_mfma_f32_16x16x32_bf16 v[20:23], v[170:173], v[194:197], v[20:23]
	v_mfma_f32_16x16x32_bf16 v[8:11], v[162:165], v[202:205], v[8:11]
	v_mfma_f32_16x16x32_bf16 v[4:7], v[170:173], v[202:205], v[4:7]
	v_mfma_f32_16x16x32_bf16 v[56:59], v[166:169], v[182:185], v[56:59]
	v_mfma_f32_16x16x32_bf16 v[52:55], v[174:177], v[182:185], v[52:55]
	v_mfma_f32_16x16x32_bf16 v[40:43], v[166:169], v[190:193], v[40:43]
	v_mfma_f32_16x16x32_bf16 v[36:39], v[174:177], v[190:193], v[36:39]
	v_mfma_f32_16x16x32_bf16 v[24:27], v[166:169], v[198:201], v[24:27]
	v_mfma_f32_16x16x32_bf16 v[20:23], v[174:177], v[198:201], v[20:23]
	v_mfma_f32_16x16x32_bf16 v[8:11], v[166:169], v[206:209], v[8:11]
	v_mfma_f32_16x16x32_bf16 v[4:7], v[174:177], v[206:209], v[4:7]
	s_setprio 0
	s_barrier
	s_add_i32 s55, s55, 2
	s_add_u32 s4, s4, 0x100
	s_addc_u32 s5, s5, 0
	s_add_u32 s53, s53, 0x100
	s_addc_u32 s54, s54, 0
	s_cmp_gt_u32 s55, 13
	s_cbranch_scc0 .LBB0_1738
	s_and_b64 vcc, exec, s[14:15]
	s_cbranch_vccz .LBB0_1741
	s_barrier

.LBB0_1874:
	s_ashr_i32 s31, s30, 31
	s_lshl_b64 s[34:35], s[30:31], 19
	s_add_u32 s34, s61, s34
	s_addc_u32 s35, s62, s35
	s_and_b64 s[44:45], s[42:43], exec
	s_cselect_b32 s31, s35, s5
	s_cselect_b32 s37, s34, s4
	s_ashr_i32 s29, s28, 31
	s_lshl_b64 s[44:45], s[28:29], 19
	s_add_u32 s44, s14, s44
	s_addc_u32 s45, s15, s45
	s_and_b64 s[52:53], s[42:43], exec
	s_cselect_b32 s29, s45, s51
	s_cselect_b32 s49, s44, s50
	s_add_u32 s4, s4, 0x40080
	s_addc_u32 s5, s5, 0
	s_add_u32 s72, s50, 0x100
	v_mov_b32_e32 v4, 0
	s_addc_u32 s73, s51, 0
	s_mov_b32 s74, -2
	v_mov_b32_e32 v5, v4
	v_mov_b32_e32 v6, v4
	v_mov_b32_e32 v7, v4
	v_mov_b32_e32 v8, v4
	v_mov_b32_e32 v9, v4
	v_mov_b32_e32 v10, v4
	v_mov_b32_e32 v11, v4
	v_mov_b32_e32 v20, v4
	v_mov_b32_e32 v21, v4
	v_mov_b32_e32 v22, v4
	v_mov_b32_e32 v23, v4
	v_mov_b32_e32 v24, v4
	v_mov_b32_e32 v25, v4
	v_mov_b32_e32 v26, v4
	v_mov_b32_e32 v27, v4
	v_mov_b32_e32 v36, v4
	v_mov_b32_e32 v37, v4
	v_mov_b32_e32 v38, v4
	v_mov_b32_e32 v39, v4
	v_mov_b32_e32 v40, v4
	v_mov_b32_e32 v41, v4
	v_mov_b32_e32 v42, v4
	v_mov_b32_e32 v43, v4
	v_mov_b32_e32 v52, v4
	v_mov_b32_e32 v53, v4
	v_mov_b32_e32 v54, v4
	v_mov_b32_e32 v55, v4
	v_mov_b32_e32 v56, v4
	v_mov_b32_e32 v57, v4
	v_mov_b32_e32 v58, v4
	v_mov_b32_e32 v59, v4
	v_mov_b32_e32 v12, v4
	v_mov_b32_e32 v13, v4
	v_mov_b32_e32 v14, v4
	v_mov_b32_e32 v15, v4
	v_mov_b32_e32 v16, v4
	v_mov_b32_e32 v17, v4
	v_mov_b32_e32 v18, v4
	v_mov_b32_e32 v19, v4
	v_mov_b32_e32 v28, v4
	v_mov_b32_e32 v29, v4
	v_mov_b32_e32 v30, v4
	v_mov_b32_e32 v31, v4
	v_mov_b32_e32 v32, v4
	v_mov_b32_e32 v33, v4
	v_mov_b32_e32 v34, v4
	v_mov_b32_e32 v35, v4
	v_mov_b32_e32 v44, v4
	v_mov_b32_e32 v45, v4
	v_mov_b32_e32 v46, v4
	v_mov_b32_e32 v47, v4
	v_mov_b32_e32 v48, v4
	v_mov_b32_e32 v49, v4
	v_mov_b32_e32 v50, v4
	v_mov_b32_e32 v51, v4
	v_mov_b32_e32 v60, v4
	v_mov_b32_e32 v61, v4
	v_mov_b32_e32 v62, v4
	v_mov_b32_e32 v63, v4
	v_mov_b32_e32 v64, v4
	v_mov_b32_e32 v65, v4
	v_mov_b32_e32 v66, v4
	v_mov_b32_e32 v67, v4
	v_mov_b32_e32 v68, v4
	v_mov_b32_e32 v69, v4
	v_mov_b32_e32 v70, v4
	v_mov_b32_e32 v71, v4
	v_mov_b32_e32 v72, v4
	v_mov_b32_e32 v73, v4
	v_mov_b32_e32 v74, v4
	v_mov_b32_e32 v75, v4
	v_mov_b32_e32 v84, v4
	v_mov_b32_e32 v85, v4
	v_mov_b32_e32 v86, v4
	v_mov_b32_e32 v87, v4
	v_mov_b32_e32 v88, v4
	v_mov_b32_e32 v89, v4
	v_mov_b32_e32 v90, v4
	v_mov_b32_e32 v91, v4
	v_mov_b32_e32 v100, v4
	v_mov_b32_e32 v101, v4
	v_mov_b32_e32 v102, v4
	v_mov_b32_e32 v103, v4
	v_mov_b32_e32 v104, v4
	v_mov_b32_e32 v105, v4
	v_mov_b32_e32 v106, v4
	v_mov_b32_e32 v107, v4
	v_mov_b32_e32 v116, v4
	v_mov_b32_e32 v117, v4
	v_mov_b32_e32 v118, v4
	v_mov_b32_e32 v119, v4
	v_mov_b32_e32 v120, v4
	v_mov_b32_e32 v121, v4
	v_mov_b32_e32 v122, v4
	v_mov_b32_e32 v123, v4
	v_mov_b32_e32 v76, v4
	v_mov_b32_e32 v77, v4
	v_mov_b32_e32 v78, v4
	v_mov_b32_e32 v79, v4
	v_mov_b32_e32 v80, v4
	v_mov_b32_e32 v81, v4
	v_mov_b32_e32 v82, v4
	v_mov_b32_e32 v83, v4
	v_mov_b32_e32 v92, v4
	v_mov_b32_e32 v93, v4
	v_mov_b32_e32 v94, v4
	v_mov_b32_e32 v95, v4
	v_mov_b32_e32 v96, v4
	v_mov_b32_e32 v97, v4
	v_mov_b32_e32 v98, v4
	v_mov_b32_e32 v99, v4
	v_mov_b32_e32 v108, v4
	v_mov_b32_e32 v109, v4
	v_mov_b32_e32 v110, v4
	v_mov_b32_e32 v111, v4
	v_mov_b32_e32 v112, v4
	v_mov_b32_e32 v113, v4
	v_mov_b32_e32 v114, v4
	v_mov_b32_e32 v115, v4
	v_mov_b32_e32 v124, v4
	v_mov_b32_e32 v125, v4
	v_mov_b32_e32 v126, v4
	v_mov_b32_e32 v127, v4
	v_mov_b32_e32 v128, v4
	v_mov_b32_e32 v129, v4
	v_mov_b32_e32 v130, v4
	v_mov_b32_e32 v131, v4
	s_mov_b64 s[82:83], 0x80
	v_add_u32_e32 v248, 0x10000, v149
.LBB0_1875:
	s_add_u32 s50, s4, 0xfffc0080
	s_addc_u32 s51, s5, -1
	s_add_i32 s75, 0, 0x10000
	s_cmp_eq_u32 s74, 12
	s_cselect_b32 s53, s31, s51
	s_cselect_b32 s52, s37, s50
	s_cselect_b32 s51, s29, s73
	s_cselect_b32 s50, s49, s72
	s_add_i32 s78, 0, 0x14000
	ds_read_b128 v[152:155], v248
	ds_read_b128 v[156:159], v248 offset:1024
	ds_read_b128 v[160:163], v248 offset:2048
	ds_read_b128 v[164:167], v248 offset:3072
	ds_read_b128 v[168:171], v248 offset:16384
	ds_read_b128 v[172:175], v248 offset:17408
	ds_read_b128 v[176:179], v248 offset:18432
	ds_read_b128 v[180:183], v248 offset:19456
	s_add_i32 m0, s47, 0xc000
	ds_read_b128 v[184:187], v151
	ds_read_b128 v[188:191], v151 offset:1024
	ds_read_b128 v[192:195], v151 offset:2048
	ds_read_b128 v[196:199], v151 offset:3072
	ds_read_b128 v[200:203], v151 offset:4096
	ds_read_b128 v[204:207], v151 offset:5120
	ds_read_b128 v[230:233], v151 offset:6144
	ds_read_b128 v[240:243], v151 offset:7168
	global_load_lds_dwordx4 v138, s[4:5]
	s_add_i32 m0, s47, 0xe000
	s_nop 0
	global_load_lds_dwordx4 v140, s[4:5]
	s_waitcnt vmcnt(8)
	s_waitcnt lgkmcnt(0)
	s_barrier
	s_setprio 1
	s_waitcnt lgkmcnt(0)
	v_mfma_f32_16x16x32_bf16 v[128:131], v[152:155], v[184:187], v[128:131]
	v_mfma_f32_16x16x32_bf16 v[124:127], v[160:163], v[184:187], v[124:127]
	v_mfma_f32_16x16x32_bf16 v[112:115], v[152:155], v[192:195], v[112:115]
	v_mfma_f32_16x16x32_bf16 v[108:111], v[160:163], v[192:195], v[108:111]
	v_mfma_f32_16x16x32_bf16 v[96:99], v[152:155], v[200:203], v[96:99]
	v_mfma_f32_16x16x32_bf16 v[92:95], v[160:163], v[200:203], v[92:95]
	v_mfma_f32_16x16x32_bf16 v[80:83], v[152:155], v[230:233], v[80:83]
	v_mfma_f32_16x16x32_bf16 v[76:79], v[160:163], v[230:233], v[76:79]
	v_mfma_f32_16x16x32_bf16 v[128:131], v[156:159], v[188:191], v[128:131]
	v_mfma_f32_16x16x32_bf16 v[124:127], v[164:167], v[188:191], v[124:127]
	v_mfma_f32_16x16x32_bf16 v[112:115], v[156:159], v[196:199], v[112:115]
	v_mfma_f32_16x16x32_bf16 v[108:111], v[164:167], v[196:199], v[108:111]
	v_mfma_f32_16x16x32_bf16 v[96:99], v[156:159], v[204:207], v[96:99]
	v_mfma_f32_16x16x32_bf16 v[92:95], v[164:167], v[204:207], v[92:95]
	v_mfma_f32_16x16x32_bf16 v[80:83], v[156:159], v[240:243], v[80:83]
	v_mfma_f32_16x16x32_bf16 v[76:79], v[164:167], v[240:243], v[76:79]
	s_setprio 0
	s_setprio 1
	v_mfma_f32_16x16x32_bf16 v[120:123], v[168:171], v[184:187], v[120:123]
	v_mfma_f32_16x16x32_bf16 v[116:119], v[176:179], v[184:187], v[116:119]
	v_mfma_f32_16x16x32_bf16 v[104:107], v[168:171], v[192:195], v[104:107]
	v_mfma_f32_16x16x32_bf16 v[100:103], v[176:179], v[192:195], v[100:103]
	v_mfma_f32_16x16x32_bf16 v[88:91], v[168:171], v[200:203], v[88:91]
	v_mfma_f32_16x16x32_bf16 v[84:87], v[176:179], v[200:203], v[84:87]
	v_mfma_f32_16x16x32_bf16 v[72:75], v[168:171], v[230:233], v[72:75]
	v_mfma_f32_16x16x32_bf16 v[68:71], v[176:179], v[230:233], v[68:71]
	v_mfma_f32_16x16x32_bf16 v[120:123], v[172:175], v[188:191], v[120:123]
	v_mfma_f32_16x16x32_bf16 v[116:119], v[180:183], v[188:191], v[116:119]
	v_mfma_f32_16x16x32_bf16 v[104:107], v[172:175], v[196:199], v[104:107]
	v_mfma_f32_16x16x32_bf16 v[100:103], v[180:183], v[196:199], v[100:103]
	v_mfma_f32_16x16x32_bf16 v[88:91], v[172:175], v[204:207], v[88:91]
	v_mfma_f32_16x16x32_bf16 v[84:87], v[180:183], v[204:207], v[84:87]
	v_mfma_f32_16x16x32_bf16 v[72:75], v[172:175], v[240:243], v[72:75]
	v_mfma_f32_16x16x32_bf16 v[68:71], v[180:183], v[240:243], v[68:71]
	s_setprio 0
	s_barrier
	s_add_i32 s75, s75, s60
	v_lshl_add_u64 v[142:143], s[50:51], 0, v[132:133]
	s_mov_b32 m0, s75
	ds_read_b128 v[184:187], v151 offset:16384
	ds_read_b128 v[188:191], v151 offset:17408
	ds_read_b128 v[192:195], v151 offset:18432
	ds_read_b128 v[196:199], v151 offset:19456
	ds_read_b128 v[200:203], v151 offset:20480
	ds_read_b128 v[204:207], v151 offset:21504
	ds_read_b128 v[230:233], v151 offset:22528
	ds_read_b128 v[240:243], v151 offset:23552
	global_load_lds_dwordx4 v[142:143], off
	s_add_i32 m0, s75, 0x2000
	s_add_u32 s76, s50, 0x40000
	v_lshl_add_u64 v[208:209], s[50:51], 0, v[136:137]
	s_addc_u32 s77, s51, 0
	s_add_i32 s75, s78, s60
	global_load_lds_dwordx4 v[208:209], off
	s_mov_b32 m0, s75
	v_lshl_add_u64 v[244:245], s[52:53], 0, v[134:135]
	global_load_lds_dwordx4 v132, s[76:77]
	s_add_i32 m0, s75, 0x2000
	s_nop 0
	global_load_lds_dwordx4 v136, s[76:77]
	v_lshl_add_u64 v[234:235], s[52:53], 0, v[0:1]
	s_mov_b32 m0, s47
	s_nop 0
	global_load_lds_dwordx4 v[234:235], off
	s_mov_b32 m0, s63
	s_nop 0
	global_load_lds_dwordx4 v[244:245], off
	s_waitcnt vmcnt(8)
	s_waitcnt lgkmcnt(0)
	s_barrier
	s_setprio 1
	s_waitcnt lgkmcnt(0)
	v_mfma_f32_16x16x32_bf16 v[64:67], v[152:155], v[184:187], v[64:67]
	v_mfma_f32_16x16x32_bf16 v[60:63], v[160:163], v[184:187], v[60:63]
	v_mfma_f32_16x16x32_bf16 v[48:51], v[152:155], v[192:195], v[48:51]
	v_mfma_f32_16x16x32_bf16 v[44:47], v[160:163], v[192:195], v[44:47]
	v_mfma_f32_16x16x32_bf16 v[32:35], v[152:155], v[200:203], v[32:35]
	v_mfma_f32_16x16x32_bf16 v[28:31], v[160:163], v[200:203], v[28:31]
	v_mfma_f32_16x16x32_bf16 v[16:19], v[152:155], v[230:233], v[16:19]
	v_mfma_f32_16x16x32_bf16 v[12:15], v[160:163], v[230:233], v[12:15]
	v_mfma_f32_16x16x32_bf16 v[64:67], v[156:159], v[188:191], v[64:67]
	v_mfma_f32_16x16x32_bf16 v[60:63], v[164:167], v[188:191], v[60:63]
	v_mfma_f32_16x16x32_bf16 v[48:51], v[156:159], v[196:199], v[48:51]
	v_mfma_f32_16x16x32_bf16 v[44:47], v[164:167], v[196:199], v[44:47]
	v_mfma_f32_16x16x32_bf16 v[32:35], v[156:159], v[204:207], v[32:35]
	v_mfma_f32_16x16x32_bf16 v[28:31], v[164:167], v[204:207], v[28:31]
	v_mfma_f32_16x16x32_bf16 v[16:19], v[156:159], v[240:243], v[16:19]
	v_mfma_f32_16x16x32_bf16 v[12:15], v[164:167], v[240:243], v[12:15]
	s_setprio 0
	s_setprio 1
	v_mfma_f32_16x16x32_bf16 v[56:59], v[168:171], v[184:187], v[56:59]
	v_mfma_f32_16x16x32_bf16 v[52:55], v[176:179], v[184:187], v[52:55]
	v_mfma_f32_16x16x32_bf16 v[40:43], v[168:171], v[192:195], v[40:43]
	v_mfma_f32_16x16x32_bf16 v[36:39], v[176:179], v[192:195], v[36:39]
	v_mfma_f32_16x16x32_bf16 v[24:27], v[168:171], v[200:203], v[24:27]
	v_mfma_f32_16x16x32_bf16 v[20:23], v[176:179], v[200:203], v[20:23]
	v_mfma_f32_16x16x32_bf16 v[8:11], v[168:171], v[230:233], v[8:11]
	v_mfma_f32_16x16x32_bf16 v[4:7], v[176:179], v[230:233], v[4:7]
	v_mfma_f32_16x16x32_bf16 v[56:59], v[172:175], v[188:191], v[56:59]
	v_mfma_f32_16x16x32_bf16 v[52:55], v[180:183], v[188:191], v[52:55]
	v_mfma_f32_16x16x32_bf16 v[40:43], v[172:175], v[196:199], v[40:43]
	v_mfma_f32_16x16x32_bf16 v[36:39], v[180:183], v[196:199], v[36:39]
	v_mfma_f32_16x16x32_bf16 v[24:27], v[172:175], v[204:207], v[24:27]
	v_mfma_f32_16x16x32_bf16 v[20:23], v[180:183], v[204:207], v[20:23]
	v_mfma_f32_16x16x32_bf16 v[8:11], v[172:175], v[240:243], v[8:11]
	v_mfma_f32_16x16x32_bf16 v[4:7], v[180:183], v[240:243], v[4:7]
	s_setprio 0
	s_barrier
	s_add_i32 s75, 0, 0x18000
	s_add_i32 s76, 0, 0x1c000
	ds_read_b128 v[152:155], v248 offset:32768
	ds_read_b128 v[156:159], v248 offset:33792
	ds_read_b128 v[160:163], v248 offset:34816
	ds_read_b128 v[164:167], v248 offset:35840
	ds_read_b128 v[168:171], v248 offset:49152
	ds_read_b128 v[172:175], v248 offset:50176
	ds_read_b128 v[176:179], v248 offset:51200
	ds_read_b128 v[180:183], v248 offset:52224
	s_add_u32 s52, s52, 0x40000
	s_addc_u32 s53, s53, 0
	s_mov_b32 m0, s64
	ds_read_b128 v[184:187], v151 offset:32768
	ds_read_b128 v[188:191], v151 offset:33792
	ds_read_b128 v[192:195], v151 offset:34816
	ds_read_b128 v[196:199], v151 offset:35840
	ds_read_b128 v[200:203], v151 offset:36864
	ds_read_b128 v[204:207], v151 offset:37888
	ds_read_b128 v[230:233], v151 offset:38912
	ds_read_b128 v[240:243], v151 offset:39936
	global_load_lds_dwordx4 v0, s[52:53]
	s_mov_b32 m0, s65
	s_nop 0
	global_load_lds_dwordx4 v134, s[52:53]
	s_waitcnt vmcnt(8)
	s_waitcnt lgkmcnt(0)
	s_barrier
	s_setprio 1
	s_waitcnt lgkmcnt(0)
	v_mfma_f32_16x16x32_bf16 v[128:131], v[152:155], v[184:187], v[128:131]
	v_mfma_f32_16x16x32_bf16 v[124:127], v[160:163], v[184:187], v[124:127]
	v_mfma_f32_16x16x32_bf16 v[112:115], v[152:155], v[192:195], v[112:115]
	v_mfma_f32_16x16x32_bf16 v[108:111], v[160:163], v[192:195], v[108:111]
	v_mfma_f32_16x16x32_bf16 v[96:99], v[152:155], v[200:203], v[96:99]
	v_mfma_f32_16x16x32_bf16 v[92:95], v[160:163], v[200:203], v[92:95]
	v_mfma_f32_16x16x32_bf16 v[80:83], v[152:155], v[230:233], v[80:83]
	v_mfma_f32_16x16x32_bf16 v[76:79], v[160:163], v[230:233], v[76:79]
	v_mfma_f32_16x16x32_bf16 v[128:131], v[156:159], v[188:191], v[128:131]
	v_mfma_f32_16x16x32_bf16 v[124:127], v[164:167], v[188:191], v[124:127]
	v_mfma_f32_16x16x32_bf16 v[112:115], v[156:159], v[196:199], v[112:115]
	v_mfma_f32_16x16x32_bf16 v[108:111], v[164:167], v[196:199], v[108:111]
	v_mfma_f32_16x16x32_bf16 v[96:99], v[156:159], v[204:207], v[96:99]
	v_mfma_f32_16x16x32_bf16 v[92:95], v[164:167], v[204:207], v[92:95]
	v_mfma_f32_16x16x32_bf16 v[80:83], v[156:159], v[240:243], v[80:83]
	v_mfma_f32_16x16x32_bf16 v[76:79], v[164:167], v[240:243], v[76:79]
	s_setprio 0
	s_setprio 1
	v_mfma_f32_16x16x32_bf16 v[120:123], v[168:171], v[184:187], v[120:123]
	v_mfma_f32_16x16x32_bf16 v[116:119], v[176:179], v[184:187], v[116:119]
	v_mfma_f32_16x16x32_bf16 v[104:107], v[168:171], v[192:195], v[104:107]
	v_mfma_f32_16x16x32_bf16 v[100:103], v[176:179], v[192:195], v[100:103]
	v_mfma_f32_16x16x32_bf16 v[88:91], v[168:171], v[200:203], v[88:91]
	v_mfma_f32_16x16x32_bf16 v[84:87], v[176:179], v[200:203], v[84:87]
	v_mfma_f32_16x16x32_bf16 v[72:75], v[168:171], v[230:233], v[72:75]
	v_mfma_f32_16x16x32_bf16 v[68:71], v[176:179], v[230:233], v[68:71]
	v_mfma_f32_16x16x32_bf16 v[120:123], v[172:175], v[188:191], v[120:123]
	v_mfma_f32_16x16x32_bf16 v[116:119], v[180:183], v[188:191], v[116:119]
	v_mfma_f32_16x16x32_bf16 v[104:107], v[172:175], v[196:199], v[104:107]
	v_mfma_f32_16x16x32_bf16 v[100:103], v[180:183], v[196:199], v[100:103]
	v_mfma_f32_16x16x32_bf16 v[88:91], v[172:175], v[204:207], v[88:91]
	v_mfma_f32_16x16x32_bf16 v[84:87], v[180:183], v[204:207], v[84:87]
	v_mfma_f32_16x16x32_bf16 v[72:75], v[172:175], v[240:243], v[72:75]
	v_mfma_f32_16x16x32_bf16 v[68:71], v[180:183], v[240:243], v[68:71]
	s_setprio 0
	s_barrier
	s_add_i32 s52, s75, s60
	v_lshl_add_u64 v[142:143], v[142:143], 0, s[82:83]
	s_mov_b32 m0, s52
	ds_read_b128 v[184:187], v151 offset:49152
	ds_read_b128 v[188:191], v151 offset:50176
	ds_read_b128 v[192:195], v151 offset:51200
	ds_read_b128 v[196:199], v151 offset:52224
	ds_read_b128 v[200:203], v151 offset:53248
	ds_read_b128 v[204:207], v151 offset:54272
	ds_read_b128 v[230:233], v151 offset:55296
	ds_read_b128 v[240:243], v151 offset:56320
	global_load_lds_dwordx4 v[142:143], off
	s_add_i32 m0, s52, 0x2000
	s_add_u32 s50, s50, 0x40080
	v_lshl_add_u64 v[142:143], v[208:209], 0, s[82:83]
	s_addc_u32 s51, s51, 0
	s_add_i32 s52, s76, s60
	global_load_lds_dwordx4 v[142:143], off
	s_mov_b32 m0, s52
	s_nop 0
	global_load_lds_dwordx4 v132, s[50:51]
	s_add_i32 m0, s52, 0x2000
	s_nop 0
	global_load_lds_dwordx4 v136, s[50:51]
	v_lshl_add_u64 v[142:143], v[234:235], 0, s[82:83]
	s_mov_b32 m0, s68
	s_nop 0
	global_load_lds_dwordx4 v[142:143], off
	v_lshl_add_u64 v[142:143], v[244:245], 0, s[82:83]
	s_mov_b32 m0, s69
	s_nop 0
	global_load_lds_dwordx4 v[142:143], off
	s_waitcnt vmcnt(8)
	s_waitcnt lgkmcnt(0)
	s_barrier
	s_setprio 1
	s_waitcnt lgkmcnt(0)
	v_mfma_f32_16x16x32_bf16 v[64:67], v[152:155], v[184:187], v[64:67]
	v_mfma_f32_16x16x32_bf16 v[60:63], v[160:163], v[184:187], v[60:63]
	v_mfma_f32_16x16x32_bf16 v[48:51], v[152:155], v[192:195], v[48:51]
	v_mfma_f32_16x16x32_bf16 v[44:47], v[160:163], v[192:195], v[44:47]
	v_mfma_f32_16x16x32_bf16 v[32:35], v[152:155], v[200:203], v[32:35]
	v_mfma_f32_16x16x32_bf16 v[28:31], v[160:163], v[200:203], v[28:31]
	v_mfma_f32_16x16x32_bf16 v[16:19], v[152:155], v[230:233], v[16:19]
	v_mfma_f32_16x16x32_bf16 v[12:15], v[160:163], v[230:233], v[12:15]
	v_mfma_f32_16x16x32_bf16 v[64:67], v[156:159], v[188:191], v[64:67]
	v_mfma_f32_16x16x32_bf16 v[60:63], v[164:167], v[188:191], v[60:63]
	v_mfma_f32_16x16x32_bf16 v[48:51], v[156:159], v[196:199], v[48:51]
	v_mfma_f32_16x16x32_bf16 v[44:47], v[164:167], v[196:199], v[44:47]
	v_mfma_f32_16x16x32_bf16 v[32:35], v[156:159], v[204:207], v[32:35]
	v_mfma_f32_16x16x32_bf16 v[28:31], v[164:167], v[204:207], v[28:31]
	v_mfma_f32_16x16x32_bf16 v[16:19], v[156:159], v[240:243], v[16:19]
	v_mfma_f32_16x16x32_bf16 v[12:15], v[164:167], v[240:243], v[12:15]
	s_setprio 0
	s_setprio 1
	v_mfma_f32_16x16x32_bf16 v[56:59], v[168:171], v[184:187], v[56:59]
	v_mfma_f32_16x16x32_bf16 v[52:55], v[176:179], v[184:187], v[52:55]
	v_mfma_f32_16x16x32_bf16 v[40:43], v[168:171], v[192:195], v[40:43]
	v_mfma_f32_16x16x32_bf16 v[36:39], v[176:179], v[192:195], v[36:39]
	v_mfma_f32_16x16x32_bf16 v[24:27], v[168:171], v[200:203], v[24:27]
	v_mfma_f32_16x16x32_bf16 v[20:23], v[176:179], v[200:203], v[20:23]
	v_mfma_f32_16x16x32_bf16 v[8:11], v[168:171], v[230:233], v[8:11]
	v_mfma_f32_16x16x32_bf16 v[4:7], v[176:179], v[230:233], v[4:7]
	v_mfma_f32_16x16x32_bf16 v[56:59], v[172:175], v[188:191], v[56:59]
	v_mfma_f32_16x16x32_bf16 v[52:55], v[180:183], v[188:191], v[52:55]
	v_mfma_f32_16x16x32_bf16 v[40:43], v[172:175], v[196:199], v[40:43]
	v_mfma_f32_16x16x32_bf16 v[36:39], v[180:183], v[196:199], v[36:39]
	v_mfma_f32_16x16x32_bf16 v[24:27], v[172:175], v[204:207], v[24:27]
	v_mfma_f32_16x16x32_bf16 v[20:23], v[180:183], v[204:207], v[20:23]
	v_mfma_f32_16x16x32_bf16 v[8:11], v[172:175], v[240:243], v[8:11]
	v_mfma_f32_16x16x32_bf16 v[4:7], v[180:183], v[240:243], v[4:7]
	s_setprio 0
	s_barrier
	s_add_i32 s74, s74, 2
	s_add_u32 s4, s4, 0x100
	s_addc_u32 s5, s5, 0
	s_add_u32 s72, s72, 0x100
	s_addc_u32 s73, s73, 0
	s_cmp_gt_u32 s74, 13
	s_cbranch_scc0 .LBB0_1875
	s_and_b64 vcc, exec, s[22:23]
	s_cbranch_vccz .LBB0_1878
	s_barrier

.LBB0_2002:
	s_add_u32 s52, s24, 0x100
	v_mov_b32_e32 v4, 0
	s_addc_u32 s53, s25, 0
	s_mov_b32 s54, -2
	s_waitcnt lgkmcnt(0)
	v_mov_b32_e32 v5, v4
	v_mov_b32_e32 v6, v4
	v_mov_b32_e32 v7, v4
	v_mov_b32_e32 v8, v4
	v_mov_b32_e32 v9, v4
	v_mov_b32_e32 v10, v4
	v_mov_b32_e32 v11, v4
	v_mov_b32_e32 v20, v4
	v_mov_b32_e32 v21, v4
	v_mov_b32_e32 v22, v4
	v_mov_b32_e32 v23, v4
	v_mov_b32_e32 v24, v4
	v_mov_b32_e32 v25, v4
	v_mov_b32_e32 v26, v4
	v_mov_b32_e32 v27, v4
	v_mov_b32_e32 v36, v4
	v_mov_b32_e32 v37, v4
	v_mov_b32_e32 v38, v4
	v_mov_b32_e32 v39, v4
	v_mov_b32_e32 v40, v4
	v_mov_b32_e32 v41, v4
	v_mov_b32_e32 v42, v4
	v_mov_b32_e32 v43, v4
	v_mov_b32_e32 v52, v4
	v_mov_b32_e32 v53, v4
	v_mov_b32_e32 v54, v4
	v_mov_b32_e32 v55, v4
	v_mov_b32_e32 v56, v4
	v_mov_b32_e32 v57, v4
	v_mov_b32_e32 v58, v4
	v_mov_b32_e32 v59, v4
	v_mov_b32_e32 v12, v4
	v_mov_b32_e32 v13, v4
	v_mov_b32_e32 v14, v4
	v_mov_b32_e32 v15, v4
	v_mov_b32_e32 v16, v4
	v_mov_b32_e32 v17, v4
	v_mov_b32_e32 v18, v4
	v_mov_b32_e32 v19, v4
	v_mov_b32_e32 v28, v4
	v_mov_b32_e32 v29, v4
	v_mov_b32_e32 v30, v4
	v_mov_b32_e32 v31, v4
	v_mov_b32_e32 v32, v4
	v_mov_b32_e32 v33, v4
	v_mov_b32_e32 v34, v4
	v_mov_b32_e32 v35, v4
	v_mov_b32_e32 v44, v4
	v_mov_b32_e32 v45, v4
	v_mov_b32_e32 v46, v4
	v_mov_b32_e32 v47, v4
	v_mov_b32_e32 v48, v4
	v_mov_b32_e32 v49, v4
	v_mov_b32_e32 v50, v4
	v_mov_b32_e32 v51, v4
	v_mov_b32_e32 v60, v4
	v_mov_b32_e32 v61, v4
	v_mov_b32_e32 v62, v4
	v_mov_b32_e32 v63, v4
	v_mov_b32_e32 v64, v4
	v_mov_b32_e32 v65, v4
	v_mov_b32_e32 v66, v4
	v_mov_b32_e32 v67, v4
	v_mov_b32_e32 v68, v4
	v_mov_b32_e32 v69, v4
	v_mov_b32_e32 v70, v4
	v_mov_b32_e32 v71, v4
	v_mov_b32_e32 v72, v4
	v_mov_b32_e32 v73, v4
	v_mov_b32_e32 v74, v4
	v_mov_b32_e32 v75, v4
	v_mov_b32_e32 v84, v4
	v_mov_b32_e32 v85, v4
	v_mov_b32_e32 v86, v4
	v_mov_b32_e32 v87, v4
	v_mov_b32_e32 v88, v4
	v_mov_b32_e32 v89, v4
	v_mov_b32_e32 v90, v4
	v_mov_b32_e32 v91, v4
	v_mov_b32_e32 v100, v4
	v_mov_b32_e32 v101, v4
	v_mov_b32_e32 v102, v4
	v_mov_b32_e32 v103, v4
	v_mov_b32_e32 v104, v4
	v_mov_b32_e32 v105, v4
	v_mov_b32_e32 v106, v4
	v_mov_b32_e32 v107, v4
	v_mov_b32_e32 v116, v4
	v_mov_b32_e32 v117, v4
	v_mov_b32_e32 v118, v4
	v_mov_b32_e32 v119, v4
	v_mov_b32_e32 v120, v4
	v_mov_b32_e32 v121, v4
	v_mov_b32_e32 v122, v4
	v_mov_b32_e32 v123, v4
	v_mov_b32_e32 v76, v4
	v_mov_b32_e32 v77, v4
	v_mov_b32_e32 v78, v4
	v_mov_b32_e32 v79, v4
	v_mov_b32_e32 v80, v4
	v_mov_b32_e32 v81, v4
	v_mov_b32_e32 v82, v4
	v_mov_b32_e32 v83, v4
	v_mov_b32_e32 v92, v4
	v_mov_b32_e32 v93, v4
	v_mov_b32_e32 v94, v4
	v_mov_b32_e32 v95, v4
	v_mov_b32_e32 v96, v4
	v_mov_b32_e32 v97, v4
	v_mov_b32_e32 v98, v4
	v_mov_b32_e32 v99, v4
	v_mov_b32_e32 v108, v4
	v_mov_b32_e32 v109, v4
	v_mov_b32_e32 v110, v4
	v_mov_b32_e32 v111, v4
	v_mov_b32_e32 v112, v4
	v_mov_b32_e32 v113, v4
	v_mov_b32_e32 v114, v4
	v_mov_b32_e32 v115, v4
	v_mov_b32_e32 v124, v4
	v_mov_b32_e32 v125, v4
	v_mov_b32_e32 v126, v4
	v_mov_b32_e32 v127, v4
	v_mov_b32_e32 v128, v4
	v_mov_b32_e32 v129, v4
	v_mov_b32_e32 v130, v4
	v_mov_b32_e32 v131, v4
	s_mov_b64 s[58:59], 0x80
	v_add_u32_e32 v248, 0x10000, v155
.LBB0_2003:
	s_add_u32 s24, s6, 0x100
	s_addc_u32 s25, s7, 0
	s_add_i32 s55, 0, 0x10000
	s_cmp_eq_u32 s54, 40
	s_cselect_b32 s29, s21, s25
	s_cselect_b32 s28, s20, s24
	s_cselect_b32 s27, s23, s53
	s_cselect_b32 s26, s22, s52
	s_add_i32 s56, 0, 0x14000
	ds_read_b128 v[132:135], v248
	ds_read_b128 v[136:139], v248 offset:1024
	ds_read_b128 v[150:153], v248 offset:2048
	ds_read_b128 v[158:161], v248 offset:3072
	ds_read_b128 v[162:165], v248 offset:16384
	ds_read_b128 v[166:169], v248 offset:17408
	ds_read_b128 v[170:173], v248 offset:18432
	ds_read_b128 v[174:177], v248 offset:19456
	v_lshl_add_u64 v[230:231], s[6:7], 0, v[146:147]
	s_add_i32 m0, s40, 0xc000
	ds_read_b128 v[178:181], v156
	ds_read_b128 v[182:185], v156 offset:1024
	ds_read_b128 v[186:189], v156 offset:2048
	ds_read_b128 v[190:193], v156 offset:3072
	ds_read_b128 v[194:197], v156 offset:4096
	ds_read_b128 v[198:201], v156 offset:5120
	ds_read_b128 v[202:205], v156 offset:6144
	ds_read_b128 v[206:209], v156 offset:7168
	global_load_lds_dwordx4 v[230:231], off
	v_lshl_add_u64 v[230:231], s[6:7], 0, v[148:149]
	s_add_i32 m0, s40, 0xe000
	s_nop 0
	global_load_lds_dwordx4 v[230:231], off
	s_waitcnt vmcnt(8)
	s_waitcnt lgkmcnt(0)
	s_barrier
	s_setprio 1
	s_waitcnt lgkmcnt(0)
	v_mfma_f32_16x16x32_bf16 v[128:131], v[132:135], v[178:181], v[128:131]
	v_mfma_f32_16x16x32_bf16 v[124:127], v[150:153], v[178:181], v[124:127]
	v_mfma_f32_16x16x32_bf16 v[112:115], v[132:135], v[186:189], v[112:115]
	v_mfma_f32_16x16x32_bf16 v[108:111], v[150:153], v[186:189], v[108:111]
	v_mfma_f32_16x16x32_bf16 v[96:99], v[132:135], v[194:197], v[96:99]
	v_mfma_f32_16x16x32_bf16 v[92:95], v[150:153], v[194:197], v[92:95]
	v_mfma_f32_16x16x32_bf16 v[80:83], v[132:135], v[202:205], v[80:83]
	v_mfma_f32_16x16x32_bf16 v[76:79], v[150:153], v[202:205], v[76:79]
	v_mfma_f32_16x16x32_bf16 v[128:131], v[136:139], v[182:185], v[128:131]
	v_mfma_f32_16x16x32_bf16 v[124:127], v[158:161], v[182:185], v[124:127]
	v_mfma_f32_16x16x32_bf16 v[112:115], v[136:139], v[190:193], v[112:115]
	v_mfma_f32_16x16x32_bf16 v[108:111], v[158:161], v[190:193], v[108:111]
	v_mfma_f32_16x16x32_bf16 v[96:99], v[136:139], v[198:201], v[96:99]
	v_mfma_f32_16x16x32_bf16 v[92:95], v[158:161], v[198:201], v[92:95]
	v_mfma_f32_16x16x32_bf16 v[80:83], v[136:139], v[206:209], v[80:83]
	v_mfma_f32_16x16x32_bf16 v[76:79], v[158:161], v[206:209], v[76:79]
	s_setprio 0
	s_setprio 1
	v_mfma_f32_16x16x32_bf16 v[120:123], v[162:165], v[178:181], v[120:123]
	v_mfma_f32_16x16x32_bf16 v[116:119], v[170:173], v[178:181], v[116:119]
	v_mfma_f32_16x16x32_bf16 v[104:107], v[162:165], v[186:189], v[104:107]
	v_mfma_f32_16x16x32_bf16 v[100:103], v[170:173], v[186:189], v[100:103]
	v_mfma_f32_16x16x32_bf16 v[88:91], v[162:165], v[194:197], v[88:91]
	v_mfma_f32_16x16x32_bf16 v[84:87], v[170:173], v[194:197], v[84:87]
	v_mfma_f32_16x16x32_bf16 v[72:75], v[162:165], v[202:205], v[72:75]
	v_mfma_f32_16x16x32_bf16 v[68:71], v[170:173], v[202:205], v[68:71]
	v_mfma_f32_16x16x32_bf16 v[120:123], v[166:169], v[182:185], v[120:123]
	v_mfma_f32_16x16x32_bf16 v[116:119], v[174:177], v[182:185], v[116:119]
	v_mfma_f32_16x16x32_bf16 v[104:107], v[166:169], v[190:193], v[104:107]
	v_mfma_f32_16x16x32_bf16 v[100:103], v[174:177], v[190:193], v[100:103]
	v_mfma_f32_16x16x32_bf16 v[88:91], v[166:169], v[198:201], v[88:91]
	v_mfma_f32_16x16x32_bf16 v[84:87], v[174:177], v[198:201], v[84:87]
	v_mfma_f32_16x16x32_bf16 v[72:75], v[166:169], v[206:209], v[72:75]
	v_mfma_f32_16x16x32_bf16 v[68:71], v[174:177], v[206:209], v[68:71]
	s_setprio 0
	s_barrier
	s_add_i32 s6, s55, s39
	v_lshl_add_u64 v[230:231], s[26:27], 0, v[140:141]
	s_mov_b32 m0, s6
	ds_read_b128 v[178:181], v156 offset:16384
	ds_read_b128 v[182:185], v156 offset:17408
	ds_read_b128 v[186:189], v156 offset:18432
	ds_read_b128 v[190:193], v156 offset:19456
	ds_read_b128 v[194:197], v156 offset:20480
	ds_read_b128 v[198:201], v156 offset:21504
	ds_read_b128 v[202:205], v156 offset:22528
	ds_read_b128 v[206:209], v156 offset:23552
	global_load_lds_dwordx4 v[230:231], off
	s_add_i32 m0, s6, 0x2000
	s_add_u32 s6, s26, 0xb0000
	v_lshl_add_u64 v[232:233], s[26:27], 0, v[144:145]
	s_addc_u32 s7, s27, 0
	s_add_i32 s55, s56, s39
	global_load_lds_dwordx4 v[232:233], off
	s_mov_b32 m0, s55
	v_lshl_add_u64 v[240:241], s[28:29], 0, v[142:143]
	global_load_lds_dwordx4 v140, s[6:7]
	s_add_i32 m0, s55, 0x2000
	s_nop 0
	global_load_lds_dwordx4 v144, s[6:7]
	v_lshl_add_u64 v[234:235], s[28:29], 0, v[0:1]
	s_mov_b32 m0, s40
	s_nop 0
	global_load_lds_dwordx4 v[234:235], off
	s_mov_b32 m0, s41
	s_nop 0
	global_load_lds_dwordx4 v[240:241], off
	s_waitcnt vmcnt(8)
	s_waitcnt lgkmcnt(0)
	s_barrier
	s_setprio 1
	s_waitcnt lgkmcnt(0)
	v_mfma_f32_16x16x32_bf16 v[64:67], v[132:135], v[178:181], v[64:67]
	v_mfma_f32_16x16x32_bf16 v[60:63], v[150:153], v[178:181], v[60:63]
	v_mfma_f32_16x16x32_bf16 v[48:51], v[132:135], v[186:189], v[48:51]
	v_mfma_f32_16x16x32_bf16 v[44:47], v[150:153], v[186:189], v[44:47]
	v_mfma_f32_16x16x32_bf16 v[32:35], v[132:135], v[194:197], v[32:35]
	v_mfma_f32_16x16x32_bf16 v[28:31], v[150:153], v[194:197], v[28:31]
	v_mfma_f32_16x16x32_bf16 v[16:19], v[132:135], v[202:205], v[16:19]
	v_mfma_f32_16x16x32_bf16 v[12:15], v[150:153], v[202:205], v[12:15]
	v_mfma_f32_16x16x32_bf16 v[64:67], v[136:139], v[182:185], v[64:67]
	v_mfma_f32_16x16x32_bf16 v[60:63], v[158:161], v[182:185], v[60:63]
	v_mfma_f32_16x16x32_bf16 v[48:51], v[136:139], v[190:193], v[48:51]
	v_mfma_f32_16x16x32_bf16 v[44:47], v[158:161], v[190:193], v[44:47]
	v_mfma_f32_16x16x32_bf16 v[32:35], v[136:139], v[198:201], v[32:35]
	v_mfma_f32_16x16x32_bf16 v[28:31], v[158:161], v[198:201], v[28:31]
	v_mfma_f32_16x16x32_bf16 v[16:19], v[136:139], v[206:209], v[16:19]
	v_mfma_f32_16x16x32_bf16 v[12:15], v[158:161], v[206:209], v[12:15]
	s_setprio 0
	s_setprio 1
	v_mfma_f32_16x16x32_bf16 v[56:59], v[162:165], v[178:181], v[56:59]
	v_mfma_f32_16x16x32_bf16 v[52:55], v[170:173], v[178:181], v[52:55]
	v_mfma_f32_16x16x32_bf16 v[40:43], v[162:165], v[186:189], v[40:43]
	v_mfma_f32_16x16x32_bf16 v[36:39], v[170:173], v[186:189], v[36:39]
	v_mfma_f32_16x16x32_bf16 v[24:27], v[162:165], v[194:197], v[24:27]
	v_mfma_f32_16x16x32_bf16 v[20:23], v[170:173], v[194:197], v[20:23]
	v_mfma_f32_16x16x32_bf16 v[8:11], v[162:165], v[202:205], v[8:11]
	v_mfma_f32_16x16x32_bf16 v[4:7], v[170:173], v[202:205], v[4:7]
	v_mfma_f32_16x16x32_bf16 v[56:59], v[166:169], v[182:185], v[56:59]
	v_mfma_f32_16x16x32_bf16 v[52:55], v[174:177], v[182:185], v[52:55]
	v_mfma_f32_16x16x32_bf16 v[40:43], v[166:169], v[190:193], v[40:43]
	v_mfma_f32_16x16x32_bf16 v[36:39], v[174:177], v[190:193], v[36:39]
	v_mfma_f32_16x16x32_bf16 v[24:27], v[166:169], v[198:201], v[24:27]
	v_mfma_f32_16x16x32_bf16 v[20:23], v[174:177], v[198:201], v[20:23]
	v_mfma_f32_16x16x32_bf16 v[8:11], v[166:169], v[206:209], v[8:11]
	v_mfma_f32_16x16x32_bf16 v[4:7], v[174:177], v[206:209], v[4:7]
	s_setprio 0
	s_barrier
	s_add_i32 s55, 0, 0x18000
	s_add_i32 s56, 0, 0x1c000
	ds_read_b128 v[132:135], v248 offset:32768
	ds_read_b128 v[136:139], v248 offset:33792
	ds_read_b128 v[150:153], v248 offset:34816
	ds_read_b128 v[158:161], v248 offset:35840
	ds_read_b128 v[162:165], v248 offset:49152
	ds_read_b128 v[166:169], v248 offset:50176
	ds_read_b128 v[170:173], v248 offset:51200
	ds_read_b128 v[174:177], v248 offset:52224
	s_add_u32 s6, s28, 0xb0000
	s_addc_u32 s7, s29, 0
	s_mov_b32 m0, s42
	ds_read_b128 v[178:181], v156 offset:32768
	ds_read_b128 v[182:185], v156 offset:33792
	ds_read_b128 v[186:189], v156 offset:34816
	ds_read_b128 v[190:193], v156 offset:35840
	ds_read_b128 v[194:197], v156 offset:36864
	ds_read_b128 v[198:201], v156 offset:37888
	ds_read_b128 v[202:205], v156 offset:38912
	ds_read_b128 v[206:209], v156 offset:39936
	global_load_lds_dwordx4 v0, s[6:7]
	s_mov_b32 m0, s43
	s_nop 0
	global_load_lds_dwordx4 v142, s[6:7]
	s_waitcnt vmcnt(8)
	s_waitcnt lgkmcnt(0)
	s_barrier
	s_setprio 1
	s_waitcnt lgkmcnt(0)
	v_mfma_f32_16x16x32_bf16 v[128:131], v[132:135], v[178:181], v[128:131]
	v_mfma_f32_16x16x32_bf16 v[124:127], v[150:153], v[178:181], v[124:127]
	v_mfma_f32_16x16x32_bf16 v[112:115], v[132:135], v[186:189], v[112:115]
	v_mfma_f32_16x16x32_bf16 v[108:111], v[150:153], v[186:189], v[108:111]
	v_mfma_f32_16x16x32_bf16 v[96:99], v[132:135], v[194:197], v[96:99]
	v_mfma_f32_16x16x32_bf16 v[92:95], v[150:153], v[194:197], v[92:95]
	v_mfma_f32_16x16x32_bf16 v[80:83], v[132:135], v[202:205], v[80:83]
	v_mfma_f32_16x16x32_bf16 v[76:79], v[150:153], v[202:205], v[76:79]
	v_mfma_f32_16x16x32_bf16 v[128:131], v[136:139], v[182:185], v[128:131]
	v_mfma_f32_16x16x32_bf16 v[124:127], v[158:161], v[182:185], v[124:127]
	v_mfma_f32_16x16x32_bf16 v[112:115], v[136:139], v[190:193], v[112:115]
	v_mfma_f32_16x16x32_bf16 v[108:111], v[158:161], v[190:193], v[108:111]
	v_mfma_f32_16x16x32_bf16 v[96:99], v[136:139], v[198:201], v[96:99]
	v_mfma_f32_16x16x32_bf16 v[92:95], v[158:161], v[198:201], v[92:95]
	v_mfma_f32_16x16x32_bf16 v[80:83], v[136:139], v[206:209], v[80:83]
	v_mfma_f32_16x16x32_bf16 v[76:79], v[158:161], v[206:209], v[76:79]
	s_setprio 0
	s_setprio 1
	v_mfma_f32_16x16x32_bf16 v[120:123], v[162:165], v[178:181], v[120:123]
	v_mfma_f32_16x16x32_bf16 v[116:119], v[170:173], v[178:181], v[116:119]
	v_mfma_f32_16x16x32_bf16 v[104:107], v[162:165], v[186:189], v[104:107]
	v_mfma_f32_16x16x32_bf16 v[100:103], v[170:173], v[186:189], v[100:103]
	v_mfma_f32_16x16x32_bf16 v[88:91], v[162:165], v[194:197], v[88:91]
	v_mfma_f32_16x16x32_bf16 v[84:87], v[170:173], v[194:197], v[84:87]
	v_mfma_f32_16x16x32_bf16 v[72:75], v[162:165], v[202:205], v[72:75]
	v_mfma_f32_16x16x32_bf16 v[68:71], v[170:173], v[202:205], v[68:71]
	v_mfma_f32_16x16x32_bf16 v[120:123], v[166:169], v[182:185], v[120:123]
	v_mfma_f32_16x16x32_bf16 v[116:119], v[174:177], v[182:185], v[116:119]
	v_mfma_f32_16x16x32_bf16 v[104:107], v[166:169], v[190:193], v[104:107]
	v_mfma_f32_16x16x32_bf16 v[100:103], v[174:177], v[190:193], v[100:103]
	v_mfma_f32_16x16x32_bf16 v[88:91], v[166:169], v[198:201], v[88:91]
	v_mfma_f32_16x16x32_bf16 v[84:87], v[174:177], v[198:201], v[84:87]
	v_mfma_f32_16x16x32_bf16 v[72:75], v[166:169], v[206:209], v[72:75]
	v_mfma_f32_16x16x32_bf16 v[68:71], v[174:177], v[206:209], v[68:71]
	s_setprio 0
	s_barrier
	s_add_i32 s6, s55, s39
	v_lshl_add_u64 v[230:231], v[230:231], 0, s[58:59]
	s_mov_b32 m0, s6
	ds_read_b128 v[178:181], v156 offset:49152
	ds_read_b128 v[182:185], v156 offset:50176
	ds_read_b128 v[186:189], v156 offset:51200
	ds_read_b128 v[190:193], v156 offset:52224
	ds_read_b128 v[194:197], v156 offset:53248
	ds_read_b128 v[198:201], v156 offset:54272
	ds_read_b128 v[202:205], v156 offset:55296
	ds_read_b128 v[206:209], v156 offset:56320
	global_load_lds_dwordx4 v[230:231], off
	s_add_i32 m0, s6, 0x2000
	s_add_u32 s6, s26, 0xb0080
	v_lshl_add_u64 v[230:231], v[232:233], 0, s[58:59]
	s_addc_u32 s7, s27, 0
	s_add_i32 s26, s56, s39
	global_load_lds_dwordx4 v[230:231], off
	s_mov_b32 m0, s26
	s_nop 0
	global_load_lds_dwordx4 v140, s[6:7]
	s_add_i32 m0, s26, 0x2000
	s_nop 0
	global_load_lds_dwordx4 v144, s[6:7]
	v_lshl_add_u64 v[230:231], v[234:235], 0, s[58:59]
	s_mov_b32 m0, s45
	s_nop 0
	global_load_lds_dwordx4 v[230:231], off
	v_lshl_add_u64 v[230:231], v[240:241], 0, s[58:59]
	s_mov_b32 m0, s46
	s_nop 0
	global_load_lds_dwordx4 v[230:231], off
	s_waitcnt vmcnt(8)
	s_waitcnt lgkmcnt(0)
	s_barrier
	s_setprio 1
	s_waitcnt lgkmcnt(0)
	v_mfma_f32_16x16x32_bf16 v[64:67], v[132:135], v[178:181], v[64:67]
	v_mfma_f32_16x16x32_bf16 v[60:63], v[150:153], v[178:181], v[60:63]
	v_mfma_f32_16x16x32_bf16 v[48:51], v[132:135], v[186:189], v[48:51]
	v_mfma_f32_16x16x32_bf16 v[44:47], v[150:153], v[186:189], v[44:47]
	v_mfma_f32_16x16x32_bf16 v[32:35], v[132:135], v[194:197], v[32:35]
	v_mfma_f32_16x16x32_bf16 v[28:31], v[150:153], v[194:197], v[28:31]
	v_mfma_f32_16x16x32_bf16 v[16:19], v[132:135], v[202:205], v[16:19]
	v_mfma_f32_16x16x32_bf16 v[12:15], v[150:153], v[202:205], v[12:15]
	v_mfma_f32_16x16x32_bf16 v[64:67], v[136:139], v[182:185], v[64:67]
	v_mfma_f32_16x16x32_bf16 v[60:63], v[158:161], v[182:185], v[60:63]
	v_mfma_f32_16x16x32_bf16 v[48:51], v[136:139], v[190:193], v[48:51]
	v_mfma_f32_16x16x32_bf16 v[44:47], v[158:161], v[190:193], v[44:47]
	v_mfma_f32_16x16x32_bf16 v[32:35], v[136:139], v[198:201], v[32:35]
	v_mfma_f32_16x16x32_bf16 v[28:31], v[158:161], v[198:201], v[28:31]
	v_mfma_f32_16x16x32_bf16 v[16:19], v[136:139], v[206:209], v[16:19]
	v_mfma_f32_16x16x32_bf16 v[12:15], v[158:161], v[206:209], v[12:15]
	s_setprio 0
	s_setprio 1
	v_mfma_f32_16x16x32_bf16 v[56:59], v[162:165], v[178:181], v[56:59]
	v_mfma_f32_16x16x32_bf16 v[52:55], v[170:173], v[178:181], v[52:55]
	v_mfma_f32_16x16x32_bf16 v[40:43], v[162:165], v[186:189], v[40:43]
	v_mfma_f32_16x16x32_bf16 v[36:39], v[170:173], v[186:189], v[36:39]
	v_mfma_f32_16x16x32_bf16 v[24:27], v[162:165], v[194:197], v[24:27]
	v_mfma_f32_16x16x32_bf16 v[20:23], v[170:173], v[194:197], v[20:23]
	v_mfma_f32_16x16x32_bf16 v[8:11], v[162:165], v[202:205], v[8:11]
	v_mfma_f32_16x16x32_bf16 v[4:7], v[170:173], v[202:205], v[4:7]
	v_mfma_f32_16x16x32_bf16 v[56:59], v[166:169], v[182:185], v[56:59]
	v_mfma_f32_16x16x32_bf16 v[52:55], v[174:177], v[182:185], v[52:55]
	v_mfma_f32_16x16x32_bf16 v[40:43], v[166:169], v[190:193], v[40:43]
	v_mfma_f32_16x16x32_bf16 v[36:39], v[174:177], v[190:193], v[36:39]
	v_mfma_f32_16x16x32_bf16 v[24:27], v[166:169], v[198:201], v[24:27]
	v_mfma_f32_16x16x32_bf16 v[20:23], v[174:177], v[198:201], v[20:23]
	v_mfma_f32_16x16x32_bf16 v[8:11], v[166:169], v[206:209], v[8:11]
	v_mfma_f32_16x16x32_bf16 v[4:7], v[174:177], v[206:209], v[4:7]
	s_setprio 0
	s_barrier
	s_add_i32 s54, s54, 2
	s_add_u32 s52, s52, 0x100
	s_addc_u32 s53, s53, 0
	s_cmp_gt_u32 s54, 41
	s_mov_b64 s[6:7], s[24:25]
	s_cbranch_scc0 .LBB0_2003
	s_and_b64 vcc, exec, s[18:19]
	s_cbranch_vccz .LBB0_2006
	s_barrier
